# norm phases: hand-written fast path for latent rows (8 rows per wave, 4-deep row prefetch, gain/shift in registers); down-GEMM gated-residual epilogue loads pipelined 8 deep
# speedup vs baseline: 1.0070x; 1.0038x over previous
.LBB0_221:
	s_andn2_b64 vcc, exec, s[4:5]
	s_cbranch_vccnz .LBB0_289
	v_readlane_b32 s8, v253, 2
	s_mov_b64 s[4:5], s[96:97]
	s_mov_b64 s[36:37], s[96:97]
	s_mov_b64 s[20:21], s[96:97]
	v_mov_b32_e32 v2, v0
	v_readlane_b32 s9, v253, 3
	s_load_dword s6, s[8:9], 0x0
	v_readfirstlane_b32 s7, v2
	s_ashr_i32 s10, s7, 6
	v_readlane_b32 s7, v254, 16
	s_add_i32 s7, s10, s7
	s_cmpk_gt_i32 s7, 0x43ff
	s_cbranch_scc1 .LBB0_235
	s_load_dwordx2 s[8:9], s[36:37], 0xb8
	s_waitcnt lgkmcnt(0)
	s_mul_i32 s52, s80, 0x5000
	s_load_dwordx2 s[20:21], s[20:21], 0xb8
	s_lshl_b64 s[36:37], s[52:53], 2
	s_mul_i32 s52, s80, 0xf000
	s_waitcnt lgkmcnt(0)
	s_add_u32 s8, s8, s36
	s_addc_u32 s9, s9, s37
	s_add_u32 s8, s8, 0x195d4000
	s_addc_u32 s9, s9, 0
	s_lshl_b64 s[36:37], s[52:53], 2
	s_load_dwordx2 s[38:39], s[4:5], 0xb8
	s_add_u32 s11, s20, s36
	s_addc_u32 s12, s21, s37
	s_add_u32 s54, s11, 0x194e0000
	v_and_b32_e32 v3, 63, v2
	s_addc_u32 s55, s12, 0
	v_lshlrev_b32_e32 v98, 5, v3
	s_cmp_lg_u32 s80, 0
	s_waitcnt lgkmcnt(0)
	v_lshl_add_u64 v[4:5], s[38:39], 0, v[98:99]
	s_mov_b64 s[12:13], 0x3bce8000
	s_cselect_b64 s[20:21], -1, 0
	s_lshl_b32 s36, s6, 3
	v_lshl_add_u64 v[34:35], v[4:5], 0, s[12:13]
	s_ashr_i32 s11, s10, 31
	v_readlane_b32 s12, v254, 16
	s_add_u32 s10, s12, s10
	v_readlane_b32 s12, v254, 58
	s_addc_u32 s11, s12, s11
	s_lshl_b64 s[40:41], s[10:11], 12
	s_add_u32 s38, s38, s40
	v_lshlrev_b32_e32 v4, 3, v3
	v_lshlrev_b32_e32 v98, 4, v3
	s_addc_u32 s39, s39, s41
	v_lshlrev_b32_e32 v2, 1, v3
	v_or_b32_e32 v6, 0x400, v4
	v_or_b32_e32 v8, 0x600, v4
	v_lshl_add_u64 v[10:11], s[38:39], 0, v[98:99]
	s_mov_b64 s[12:13], 0x1da24c00
	s_ashr_i32 s37, s36, 31
	v_lshl_add_u64 v[36:37], v[10:11], 0, s[12:13]
	s_lshl_b64 s[38:39], s[36:37], 12
	s_lshl_b64 s[42:43], s[10:11], 13
	s_lshl_b64 s[44:45], s[36:37], 13
	v_cndmask_b32_e64 v56, 0, 1, s[20:21]
	v_lshlrev_b32_e32 v98, 4, v2
	s_xor_b64 s[46:47], s[20:21], -1
	v_lshlrev_b32_e32 v57, 2, v4
	v_lshlrev_b32_e32 v58, 2, v6
	v_lshlrev_b32_e32 v59, 2, v8
	s_mov_b32 s101, 0
	s_cmp_lg_u32 s6, 0x100
	s_cbranch_scc1 .Lnf1_skip
	s_cmp_eq_u32 s80, 0
	s_cbranch_scc1 .Lnf1_skip
	s_mov_b32 s101, 1
	s_load_dwordx2 s[40:41], s[4:5], 0xb8
	v_and_b32_e32 v38, 63, v0
	v_lshlrev_b32_e32 v39, 4, v38
	v_lshlrev_b32_e32 v40, 5, v38
	s_lshl_b32 s10, s7, 15
	s_lshr_b32 s48, s7, 9
	s_lshl_b32 s20, s48, 13
	s_mul_i32 s49, s48, 0xc000
	s_waitcnt lgkmcnt(0)
	s_add_u32 s10, s40, s10
	s_addc_u32 s11, s41, 0
	s_add_u32 s10, s10, 0x19624000
	s_addc_u32 s11, s11, 0
	s_add_u32 s40, s8, s20
	s_addc_u32 s41, s9, 0
	s_add_u32 s48, s54, s49
	s_addc_u32 s49, s55, 0
	s_add_u32 s20, s10, 0x4400000
	s_addc_u32 s21, s11, 0
	global_load_dwordx4 v[100:103], v39, s[10:11]
	global_load_dwordx4 v[104:107], v39, s[10:11] offset:1024
	global_load_dwordx4 v[108:111], v39, s[10:11] offset:2048
	global_load_dwordx4 v[112:115], v39, s[10:11] offset:3072
	s_add_u32 s10, s10, 0x1000
	s_addc_u32 s11, s11, 0
	global_load_dwordx4 v[2:5], v40, s[40:41]
	global_load_dwordx4 v[6:9], v40, s[40:41] offset:16
	global_load_dwordx4 v[10:13], v40, s[40:41] offset:2048
	global_load_dwordx4 v[14:17], v40, s[40:41] offset:2064
	s_add_u32 s40, s40, 0x1000
	s_addc_u32 s41, s41, 0
	global_load_dwordx4 v[18:21], v40, s[40:41]
	global_load_dwordx4 v[22:25], v40, s[40:41] offset:16
	global_load_dwordx4 v[26:29], v40, s[40:41] offset:2048
	global_load_dwordx4 v[30:33], v40, s[40:41] offset:2064
	global_load_dwordx4 v[164:167], v40, s[48:49]
	global_load_dwordx4 v[168:171], v40, s[48:49] offset:16
	global_load_dwordx4 v[172:175], v40, s[48:49] offset:2048
	global_load_dwordx4 v[176:179], v40, s[48:49] offset:2064
	s_add_u32 s48, s48, 0x1000
	s_addc_u32 s49, s49, 0
	global_load_dwordx4 v[180:183], v40, s[48:49]
	global_load_dwordx4 v[184:187], v40, s[48:49] offset:16
	global_load_dwordx4 v[188:191], v40, s[48:49] offset:2048
	global_load_dwordx4 v[192:195], v40, s[48:49] offset:2064
	global_load_dwordx4 v[116:119], v39, s[10:11]
	global_load_dwordx4 v[120:123], v39, s[10:11] offset:1024
	global_load_dwordx4 v[124:127], v39, s[10:11] offset:2048
	global_load_dwordx4 v[128:131], v39, s[10:11] offset:3072
	s_add_u32 s10, s10, 0x1000
	s_addc_u32 s11, s11, 0
	global_load_dwordx4 v[132:135], v39, s[10:11]
	global_load_dwordx4 v[136:139], v39, s[10:11] offset:1024
	global_load_dwordx4 v[140:143], v39, s[10:11] offset:2048
	global_load_dwordx4 v[144:147], v39, s[10:11] offset:3072
	s_add_u32 s10, s10, 0x1000
	s_addc_u32 s11, s11, 0
	global_load_dwordx4 v[148:151], v39, s[10:11]
	global_load_dwordx4 v[152:155], v39, s[10:11] offset:1024
	global_load_dwordx4 v[156:159], v39, s[10:11] offset:2048
	global_load_dwordx4 v[160:163], v39, s[10:11] offset:3072
	s_add_u32 s10, s10, 0x1000
	s_addc_u32 s11, s11, 0
	v_mov_b32_e32 v47, 0x3a000000
	s_waitcnt vmcnt(28)
	v_lshlrev_b32_e32 v60, 16, v100
	v_and_b32_e32 v61, 0xffff0000, v100
	v_pk_mul_f32 v[42:43], v[60:61], v[60:61]
	v_lshlrev_b32_e32 v62, 16, v101
	v_and_b32_e32 v63, 0xffff0000, v101
	v_pk_fma_f32 v[42:43], v[62:63], v[62:63], v[42:43]
	v_lshlrev_b32_e32 v64, 16, v102
	v_and_b32_e32 v65, 0xffff0000, v102
	v_pk_fma_f32 v[42:43], v[64:65], v[64:65], v[42:43]
	v_lshlrev_b32_e32 v66, 16, v103
	v_and_b32_e32 v67, 0xffff0000, v103
	v_pk_fma_f32 v[42:43], v[66:67], v[66:67], v[42:43]
	v_lshlrev_b32_e32 v60, 16, v104
	v_and_b32_e32 v61, 0xffff0000, v104
	v_pk_fma_f32 v[42:43], v[60:61], v[60:61], v[42:43]
	v_lshlrev_b32_e32 v62, 16, v105
	v_and_b32_e32 v63, 0xffff0000, v105
	v_pk_fma_f32 v[42:43], v[62:63], v[62:63], v[42:43]
	v_lshlrev_b32_e32 v64, 16, v106
	v_and_b32_e32 v65, 0xffff0000, v106
	v_pk_fma_f32 v[42:43], v[64:65], v[64:65], v[42:43]
	v_lshlrev_b32_e32 v66, 16, v107
	v_and_b32_e32 v67, 0xffff0000, v107
	v_pk_fma_f32 v[42:43], v[66:67], v[66:67], v[42:43]
	v_lshlrev_b32_e32 v60, 16, v108
	v_and_b32_e32 v61, 0xffff0000, v108
	v_pk_fma_f32 v[42:43], v[60:61], v[60:61], v[42:43]
	v_lshlrev_b32_e32 v62, 16, v109
	v_and_b32_e32 v63, 0xffff0000, v109
	v_pk_fma_f32 v[42:43], v[62:63], v[62:63], v[42:43]
	v_lshlrev_b32_e32 v64, 16, v110
	v_and_b32_e32 v65, 0xffff0000, v110
	v_pk_fma_f32 v[42:43], v[64:65], v[64:65], v[42:43]
	v_lshlrev_b32_e32 v66, 16, v111
	v_and_b32_e32 v67, 0xffff0000, v111
	v_pk_fma_f32 v[42:43], v[66:67], v[66:67], v[42:43]
	v_lshlrev_b32_e32 v60, 16, v112
	v_and_b32_e32 v61, 0xffff0000, v112
	v_pk_fma_f32 v[42:43], v[60:61], v[60:61], v[42:43]
	v_lshlrev_b32_e32 v62, 16, v113
	v_and_b32_e32 v63, 0xffff0000, v113
	v_pk_fma_f32 v[42:43], v[62:63], v[62:63], v[42:43]
	v_lshlrev_b32_e32 v64, 16, v114
	v_and_b32_e32 v65, 0xffff0000, v114
	v_pk_fma_f32 v[42:43], v[64:65], v[64:65], v[42:43]
	v_lshlrev_b32_e32 v66, 16, v115
	v_and_b32_e32 v67, 0xffff0000, v115
	v_pk_fma_f32 v[42:43], v[66:67], v[66:67], v[42:43]
	v_add_f32_e32 v42, v42, v43
	s_nop 1
	v_add_f32_dpp v42, v42, v42 quad_perm:[1,0,3,2] row_mask:0xf bank_mask:0xf
	s_nop 1
	v_add_f32_dpp v42, v42, v42 quad_perm:[2,3,0,1] row_mask:0xf bank_mask:0xf
	s_nop 1
	v_add_f32_dpp v42, v42, v42 row_half_mirror row_mask:0xf bank_mask:0xf
	s_nop 1
	v_add_f32_dpp v42, v42, v42 row_mirror row_mask:0xf bank_mask:0xf
	s_nop 1
	v_add_f32_dpp v42, v42, v42 row_bcast:15 row_mask:0xa bank_mask:0xf
	s_nop 1
	v_add_f32_dpp v42, v42, v42 row_bcast:31 row_mask:0xc bank_mask:0xf
	s_nop 1
	v_readlane_b32 s100, v42, 63
	s_nop 3
	v_mov_b32_e32 v44, s100
	v_fma_f32 v44, v44, v47, v224
	v_rsq_f32_e32 v45, v44
	s_nop 0
	v_mul_f32_e32 v46, v44, v45
	v_mul_f32_e32 v46, v46, v45
	v_fmaak_f32 v46, -0.5, v46, 0x3fc00000
	v_mul_f32_e32 v44, v45, v46
	v_mov_b32_e32 v45, v44
	s_waitcnt vmcnt(12)
	v_lshlrev_b32_e32 v60, 16, v100
	v_and_b32_e32 v61, 0xffff0000, v100
	v_pk_mul_f32 v[60:61], v[60:61], v[44:45]
	v_pk_fma_f32 v[60:61], v[60:61], v[2:3], v[164:165]
	v_cvt_pk_bf16_f32 v100, v60, v61
	v_lshlrev_b32_e32 v62, 16, v101
	v_and_b32_e32 v63, 0xffff0000, v101
	v_pk_mul_f32 v[62:63], v[62:63], v[44:45]
	v_pk_fma_f32 v[62:63], v[62:63], v[4:5], v[166:167]
	v_cvt_pk_bf16_f32 v101, v62, v63
	v_lshlrev_b32_e32 v64, 16, v102
	v_and_b32_e32 v65, 0xffff0000, v102
	v_pk_mul_f32 v[64:65], v[64:65], v[44:45]
	v_pk_fma_f32 v[64:65], v[64:65], v[6:7], v[168:169]
	v_cvt_pk_bf16_f32 v102, v64, v65
	v_lshlrev_b32_e32 v66, 16, v103
	v_and_b32_e32 v67, 0xffff0000, v103
	v_pk_mul_f32 v[66:67], v[66:67], v[44:45]
	v_pk_fma_f32 v[66:67], v[66:67], v[8:9], v[170:171]
	v_cvt_pk_bf16_f32 v103, v66, v67
	v_lshlrev_b32_e32 v60, 16, v104
	v_and_b32_e32 v61, 0xffff0000, v104
	v_pk_mul_f32 v[60:61], v[60:61], v[44:45]
	v_pk_fma_f32 v[60:61], v[60:61], v[10:11], v[172:173]
	v_cvt_pk_bf16_f32 v104, v60, v61
	v_lshlrev_b32_e32 v62, 16, v105
	v_and_b32_e32 v63, 0xffff0000, v105
	v_pk_mul_f32 v[62:63], v[62:63], v[44:45]
	v_pk_fma_f32 v[62:63], v[62:63], v[12:13], v[174:175]
	v_cvt_pk_bf16_f32 v105, v62, v63
	v_lshlrev_b32_e32 v64, 16, v106
	v_and_b32_e32 v65, 0xffff0000, v106
	v_pk_mul_f32 v[64:65], v[64:65], v[44:45]
	v_pk_fma_f32 v[64:65], v[64:65], v[14:15], v[176:177]
	v_cvt_pk_bf16_f32 v106, v64, v65
	v_lshlrev_b32_e32 v66, 16, v107
	v_and_b32_e32 v67, 0xffff0000, v107
	v_pk_mul_f32 v[66:67], v[66:67], v[44:45]
	v_pk_fma_f32 v[66:67], v[66:67], v[16:17], v[178:179]
	v_cvt_pk_bf16_f32 v107, v66, v67
	v_lshlrev_b32_e32 v60, 16, v108
	v_and_b32_e32 v61, 0xffff0000, v108
	v_pk_mul_f32 v[60:61], v[60:61], v[44:45]
	v_pk_fma_f32 v[60:61], v[60:61], v[18:19], v[180:181]
	v_cvt_pk_bf16_f32 v108, v60, v61
	v_lshlrev_b32_e32 v62, 16, v109
	v_and_b32_e32 v63, 0xffff0000, v109
	v_pk_mul_f32 v[62:63], v[62:63], v[44:45]
	v_pk_fma_f32 v[62:63], v[62:63], v[20:21], v[182:183]
	v_cvt_pk_bf16_f32 v109, v62, v63
	v_lshlrev_b32_e32 v64, 16, v110
	v_and_b32_e32 v65, 0xffff0000, v110
	v_pk_mul_f32 v[64:65], v[64:65], v[44:45]
	v_pk_fma_f32 v[64:65], v[64:65], v[22:23], v[184:185]
	v_cvt_pk_bf16_f32 v110, v64, v65
	v_lshlrev_b32_e32 v66, 16, v111
	v_and_b32_e32 v67, 0xffff0000, v111
	v_pk_mul_f32 v[66:67], v[66:67], v[44:45]
	v_pk_fma_f32 v[66:67], v[66:67], v[24:25], v[186:187]
	v_cvt_pk_bf16_f32 v111, v66, v67
	v_lshlrev_b32_e32 v60, 16, v112
	v_and_b32_e32 v61, 0xffff0000, v112
	v_pk_mul_f32 v[60:61], v[60:61], v[44:45]
	v_pk_fma_f32 v[60:61], v[60:61], v[26:27], v[188:189]
	v_cvt_pk_bf16_f32 v112, v60, v61
	v_lshlrev_b32_e32 v62, 16, v113
	v_and_b32_e32 v63, 0xffff0000, v113
	v_pk_mul_f32 v[62:63], v[62:63], v[44:45]
	v_pk_fma_f32 v[62:63], v[62:63], v[28:29], v[190:191]
	v_cvt_pk_bf16_f32 v113, v62, v63
	v_lshlrev_b32_e32 v64, 16, v114
	v_and_b32_e32 v65, 0xffff0000, v114
	v_pk_mul_f32 v[64:65], v[64:65], v[44:45]
	v_pk_fma_f32 v[64:65], v[64:65], v[30:31], v[192:193]
	v_cvt_pk_bf16_f32 v114, v64, v65
	v_lshlrev_b32_e32 v66, 16, v115
	v_and_b32_e32 v67, 0xffff0000, v115
	v_pk_mul_f32 v[66:67], v[66:67], v[44:45]
	v_pk_fma_f32 v[66:67], v[66:67], v[32:33], v[194:195]
	v_cvt_pk_bf16_f32 v115, v66, v67
	global_store_dwordx4 v39, v[100:103], s[20:21]
	global_store_dwordx4 v39, v[104:107], s[20:21] offset:1024
	global_store_dwordx4 v39, v[108:111], s[20:21] offset:2048
	global_store_dwordx4 v39, v[112:115], s[20:21] offset:3072
	s_add_u32 s20, s20, 0x1000
	s_addc_u32 s21, s21, 0
	global_load_dwordx4 v[100:103], v39, s[10:11]
	global_load_dwordx4 v[104:107], v39, s[10:11] offset:1024
	global_load_dwordx4 v[108:111], v39, s[10:11] offset:2048
	global_load_dwordx4 v[112:115], v39, s[10:11] offset:3072
	s_add_u32 s10, s10, 0x1000
	s_addc_u32 s11, s11, 0
	s_waitcnt vmcnt(16)
	v_lshlrev_b32_e32 v60, 16, v116
	v_and_b32_e32 v61, 0xffff0000, v116
	v_pk_mul_f32 v[42:43], v[60:61], v[60:61]
	v_lshlrev_b32_e32 v62, 16, v117
	v_and_b32_e32 v63, 0xffff0000, v117
	v_pk_fma_f32 v[42:43], v[62:63], v[62:63], v[42:43]
	v_lshlrev_b32_e32 v64, 16, v118
	v_and_b32_e32 v65, 0xffff0000, v118
	v_pk_fma_f32 v[42:43], v[64:65], v[64:65], v[42:43]
	v_lshlrev_b32_e32 v66, 16, v119
	v_and_b32_e32 v67, 0xffff0000, v119
	v_pk_fma_f32 v[42:43], v[66:67], v[66:67], v[42:43]
	v_lshlrev_b32_e32 v60, 16, v120
	v_and_b32_e32 v61, 0xffff0000, v120
	v_pk_fma_f32 v[42:43], v[60:61], v[60:61], v[42:43]
	v_lshlrev_b32_e32 v62, 16, v121
	v_and_b32_e32 v63, 0xffff0000, v121
	v_pk_fma_f32 v[42:43], v[62:63], v[62:63], v[42:43]
	v_lshlrev_b32_e32 v64, 16, v122
	v_and_b32_e32 v65, 0xffff0000, v122
	v_pk_fma_f32 v[42:43], v[64:65], v[64:65], v[42:43]
	v_lshlrev_b32_e32 v66, 16, v123
	v_and_b32_e32 v67, 0xffff0000, v123
	v_pk_fma_f32 v[42:43], v[66:67], v[66:67], v[42:43]
	v_lshlrev_b32_e32 v60, 16, v124
	v_and_b32_e32 v61, 0xffff0000, v124
	v_pk_fma_f32 v[42:43], v[60:61], v[60:61], v[42:43]
	v_lshlrev_b32_e32 v62, 16, v125
	v_and_b32_e32 v63, 0xffff0000, v125
	v_pk_fma_f32 v[42:43], v[62:63], v[62:63], v[42:43]
	v_lshlrev_b32_e32 v64, 16, v126
	v_and_b32_e32 v65, 0xffff0000, v126
	v_pk_fma_f32 v[42:43], v[64:65], v[64:65], v[42:43]
	v_lshlrev_b32_e32 v66, 16, v127
	v_and_b32_e32 v67, 0xffff0000, v127
	v_pk_fma_f32 v[42:43], v[66:67], v[66:67], v[42:43]
	v_lshlrev_b32_e32 v60, 16, v128
	v_and_b32_e32 v61, 0xffff0000, v128
	v_pk_fma_f32 v[42:43], v[60:61], v[60:61], v[42:43]
	v_lshlrev_b32_e32 v62, 16, v129
	v_and_b32_e32 v63, 0xffff0000, v129
	v_pk_fma_f32 v[42:43], v[62:63], v[62:63], v[42:43]
	v_lshlrev_b32_e32 v64, 16, v130
	v_and_b32_e32 v65, 0xffff0000, v130
	v_pk_fma_f32 v[42:43], v[64:65], v[64:65], v[42:43]
	v_lshlrev_b32_e32 v66, 16, v131
	v_and_b32_e32 v67, 0xffff0000, v131
	v_pk_fma_f32 v[42:43], v[66:67], v[66:67], v[42:43]
	v_add_f32_e32 v42, v42, v43
	s_nop 1
	v_add_f32_dpp v42, v42, v42 quad_perm:[1,0,3,2] row_mask:0xf bank_mask:0xf
	s_nop 1
	v_add_f32_dpp v42, v42, v42 quad_perm:[2,3,0,1] row_mask:0xf bank_mask:0xf
	s_nop 1
	v_add_f32_dpp v42, v42, v42 row_half_mirror row_mask:0xf bank_mask:0xf
	s_nop 1
	v_add_f32_dpp v42, v42, v42 row_mirror row_mask:0xf bank_mask:0xf
	s_nop 1
	v_add_f32_dpp v42, v42, v42 row_bcast:15 row_mask:0xa bank_mask:0xf
	s_nop 1
	v_add_f32_dpp v42, v42, v42 row_bcast:31 row_mask:0xc bank_mask:0xf
	s_nop 1
	v_readlane_b32 s100, v42, 63
	s_nop 3
	v_mov_b32_e32 v44, s100
	v_fma_f32 v44, v44, v47, v224
	v_rsq_f32_e32 v45, v44
	s_nop 0
	v_mul_f32_e32 v46, v44, v45
	v_mul_f32_e32 v46, v46, v45
	v_fmaak_f32 v46, -0.5, v46, 0x3fc00000
	v_mul_f32_e32 v44, v45, v46
	v_mov_b32_e32 v45, v44
	v_lshlrev_b32_e32 v60, 16, v116
	v_and_b32_e32 v61, 0xffff0000, v116
	v_pk_mul_f32 v[60:61], v[60:61], v[44:45]
	v_pk_fma_f32 v[60:61], v[60:61], v[2:3], v[164:165]
	v_cvt_pk_bf16_f32 v116, v60, v61
	v_lshlrev_b32_e32 v62, 16, v117
	v_and_b32_e32 v63, 0xffff0000, v117
	v_pk_mul_f32 v[62:63], v[62:63], v[44:45]
	v_pk_fma_f32 v[62:63], v[62:63], v[4:5], v[166:167]
	v_cvt_pk_bf16_f32 v117, v62, v63
	v_lshlrev_b32_e32 v64, 16, v118
	v_and_b32_e32 v65, 0xffff0000, v118
	v_pk_mul_f32 v[64:65], v[64:65], v[44:45]
	v_pk_fma_f32 v[64:65], v[64:65], v[6:7], v[168:169]
	v_cvt_pk_bf16_f32 v118, v64, v65
	v_lshlrev_b32_e32 v66, 16, v119
	v_and_b32_e32 v67, 0xffff0000, v119
	v_pk_mul_f32 v[66:67], v[66:67], v[44:45]
	v_pk_fma_f32 v[66:67], v[66:67], v[8:9], v[170:171]
	v_cvt_pk_bf16_f32 v119, v66, v67
	v_lshlrev_b32_e32 v60, 16, v120
	v_and_b32_e32 v61, 0xffff0000, v120
	v_pk_mul_f32 v[60:61], v[60:61], v[44:45]
	v_pk_fma_f32 v[60:61], v[60:61], v[10:11], v[172:173]
	v_cvt_pk_bf16_f32 v120, v60, v61
	v_lshlrev_b32_e32 v62, 16, v121
	v_and_b32_e32 v63, 0xffff0000, v121
	v_pk_mul_f32 v[62:63], v[62:63], v[44:45]
	v_pk_fma_f32 v[62:63], v[62:63], v[12:13], v[174:175]
	v_cvt_pk_bf16_f32 v121, v62, v63
	v_lshlrev_b32_e32 v64, 16, v122
	v_and_b32_e32 v65, 0xffff0000, v122
	v_pk_mul_f32 v[64:65], v[64:65], v[44:45]
	v_pk_fma_f32 v[64:65], v[64:65], v[14:15], v[176:177]
	v_cvt_pk_bf16_f32 v122, v64, v65
	v_lshlrev_b32_e32 v66, 16, v123
	v_and_b32_e32 v67, 0xffff0000, v123
	v_pk_mul_f32 v[66:67], v[66:67], v[44:45]
	v_pk_fma_f32 v[66:67], v[66:67], v[16:17], v[178:179]
	v_cvt_pk_bf16_f32 v123, v66, v67
	v_lshlrev_b32_e32 v60, 16, v124
	v_and_b32_e32 v61, 0xffff0000, v124
	v_pk_mul_f32 v[60:61], v[60:61], v[44:45]
	v_pk_fma_f32 v[60:61], v[60:61], v[18:19], v[180:181]
	v_cvt_pk_bf16_f32 v124, v60, v61
	v_lshlrev_b32_e32 v62, 16, v125
	v_and_b32_e32 v63, 0xffff0000, v125
	v_pk_mul_f32 v[62:63], v[62:63], v[44:45]
	v_pk_fma_f32 v[62:63], v[62:63], v[20:21], v[182:183]
	v_cvt_pk_bf16_f32 v125, v62, v63
	v_lshlrev_b32_e32 v64, 16, v126
	v_and_b32_e32 v65, 0xffff0000, v126
	v_pk_mul_f32 v[64:65], v[64:65], v[44:45]
	v_pk_fma_f32 v[64:65], v[64:65], v[22:23], v[184:185]
	v_cvt_pk_bf16_f32 v126, v64, v65
	v_lshlrev_b32_e32 v66, 16, v127
	v_and_b32_e32 v67, 0xffff0000, v127
	v_pk_mul_f32 v[66:67], v[66:67], v[44:45]
	v_pk_fma_f32 v[66:67], v[66:67], v[24:25], v[186:187]
	v_cvt_pk_bf16_f32 v127, v66, v67
	v_lshlrev_b32_e32 v60, 16, v128
	v_and_b32_e32 v61, 0xffff0000, v128
	v_pk_mul_f32 v[60:61], v[60:61], v[44:45]
	v_pk_fma_f32 v[60:61], v[60:61], v[26:27], v[188:189]
	v_cvt_pk_bf16_f32 v128, v60, v61
	v_lshlrev_b32_e32 v62, 16, v129
	v_and_b32_e32 v63, 0xffff0000, v129
	v_pk_mul_f32 v[62:63], v[62:63], v[44:45]
	v_pk_fma_f32 v[62:63], v[62:63], v[28:29], v[190:191]
	v_cvt_pk_bf16_f32 v129, v62, v63
	v_lshlrev_b32_e32 v64, 16, v130
	v_and_b32_e32 v65, 0xffff0000, v130
	v_pk_mul_f32 v[64:65], v[64:65], v[44:45]
	v_pk_fma_f32 v[64:65], v[64:65], v[30:31], v[192:193]
	v_cvt_pk_bf16_f32 v130, v64, v65
	v_lshlrev_b32_e32 v66, 16, v131
	v_and_b32_e32 v67, 0xffff0000, v131
	v_pk_mul_f32 v[66:67], v[66:67], v[44:45]
	v_pk_fma_f32 v[66:67], v[66:67], v[32:33], v[194:195]
	v_cvt_pk_bf16_f32 v131, v66, v67
	global_store_dwordx4 v39, v[116:119], s[20:21]
	global_store_dwordx4 v39, v[120:123], s[20:21] offset:1024
	global_store_dwordx4 v39, v[124:127], s[20:21] offset:2048
	global_store_dwordx4 v39, v[128:131], s[20:21] offset:3072
	s_add_u32 s20, s20, 0x1000
	s_addc_u32 s21, s21, 0
	global_load_dwordx4 v[116:119], v39, s[10:11]
	global_load_dwordx4 v[120:123], v39, s[10:11] offset:1024
	global_load_dwordx4 v[124:127], v39, s[10:11] offset:2048
	global_load_dwordx4 v[128:131], v39, s[10:11] offset:3072
	s_add_u32 s10, s10, 0x1000
	s_addc_u32 s11, s11, 0
	s_waitcnt vmcnt(20)
	v_lshlrev_b32_e32 v60, 16, v132
	v_and_b32_e32 v61, 0xffff0000, v132
	v_pk_mul_f32 v[42:43], v[60:61], v[60:61]
	v_lshlrev_b32_e32 v62, 16, v133
	v_and_b32_e32 v63, 0xffff0000, v133
	v_pk_fma_f32 v[42:43], v[62:63], v[62:63], v[42:43]
	v_lshlrev_b32_e32 v64, 16, v134
	v_and_b32_e32 v65, 0xffff0000, v134
	v_pk_fma_f32 v[42:43], v[64:65], v[64:65], v[42:43]
	v_lshlrev_b32_e32 v66, 16, v135
	v_and_b32_e32 v67, 0xffff0000, v135
	v_pk_fma_f32 v[42:43], v[66:67], v[66:67], v[42:43]
	v_lshlrev_b32_e32 v60, 16, v136
	v_and_b32_e32 v61, 0xffff0000, v136
	v_pk_fma_f32 v[42:43], v[60:61], v[60:61], v[42:43]
	v_lshlrev_b32_e32 v62, 16, v137
	v_and_b32_e32 v63, 0xffff0000, v137
	v_pk_fma_f32 v[42:43], v[62:63], v[62:63], v[42:43]
	v_lshlrev_b32_e32 v64, 16, v138
	v_and_b32_e32 v65, 0xffff0000, v138
	v_pk_fma_f32 v[42:43], v[64:65], v[64:65], v[42:43]
	v_lshlrev_b32_e32 v66, 16, v139
	v_and_b32_e32 v67, 0xffff0000, v139
	v_pk_fma_f32 v[42:43], v[66:67], v[66:67], v[42:43]
	v_lshlrev_b32_e32 v60, 16, v140
	v_and_b32_e32 v61, 0xffff0000, v140
	v_pk_fma_f32 v[42:43], v[60:61], v[60:61], v[42:43]
	v_lshlrev_b32_e32 v62, 16, v141
	v_and_b32_e32 v63, 0xffff0000, v141
	v_pk_fma_f32 v[42:43], v[62:63], v[62:63], v[42:43]
	v_lshlrev_b32_e32 v64, 16, v142
	v_and_b32_e32 v65, 0xffff0000, v142
	v_pk_fma_f32 v[42:43], v[64:65], v[64:65], v[42:43]
	v_lshlrev_b32_e32 v66, 16, v143
	v_and_b32_e32 v67, 0xffff0000, v143
	v_pk_fma_f32 v[42:43], v[66:67], v[66:67], v[42:43]
	v_lshlrev_b32_e32 v60, 16, v144
	v_and_b32_e32 v61, 0xffff0000, v144
	v_pk_fma_f32 v[42:43], v[60:61], v[60:61], v[42:43]
	v_lshlrev_b32_e32 v62, 16, v145
	v_and_b32_e32 v63, 0xffff0000, v145
	v_pk_fma_f32 v[42:43], v[62:63], v[62:63], v[42:43]
	v_lshlrev_b32_e32 v64, 16, v146
	v_and_b32_e32 v65, 0xffff0000, v146
	v_pk_fma_f32 v[42:43], v[64:65], v[64:65], v[42:43]
	v_lshlrev_b32_e32 v66, 16, v147
	v_and_b32_e32 v67, 0xffff0000, v147
	v_pk_fma_f32 v[42:43], v[66:67], v[66:67], v[42:43]
	v_add_f32_e32 v42, v42, v43
	s_nop 1
	v_add_f32_dpp v42, v42, v42 quad_perm:[1,0,3,2] row_mask:0xf bank_mask:0xf
	s_nop 1
	v_add_f32_dpp v42, v42, v42 quad_perm:[2,3,0,1] row_mask:0xf bank_mask:0xf
	s_nop 1
	v_add_f32_dpp v42, v42, v42 row_half_mirror row_mask:0xf bank_mask:0xf
	s_nop 1
	v_add_f32_dpp v42, v42, v42 row_mirror row_mask:0xf bank_mask:0xf
	s_nop 1
	v_add_f32_dpp v42, v42, v42 row_bcast:15 row_mask:0xa bank_mask:0xf
	s_nop 1
	v_add_f32_dpp v42, v42, v42 row_bcast:31 row_mask:0xc bank_mask:0xf
	s_nop 1
	v_readlane_b32 s100, v42, 63
	s_nop 3
	v_mov_b32_e32 v44, s100
	v_fma_f32 v44, v44, v47, v224
	v_rsq_f32_e32 v45, v44
	s_nop 0
	v_mul_f32_e32 v46, v44, v45
	v_mul_f32_e32 v46, v46, v45
	v_fmaak_f32 v46, -0.5, v46, 0x3fc00000
	v_mul_f32_e32 v44, v45, v46
	v_mov_b32_e32 v45, v44
	v_lshlrev_b32_e32 v60, 16, v132
	v_and_b32_e32 v61, 0xffff0000, v132
	v_pk_mul_f32 v[60:61], v[60:61], v[44:45]
	v_pk_fma_f32 v[60:61], v[60:61], v[2:3], v[164:165]
	v_cvt_pk_bf16_f32 v132, v60, v61
	v_lshlrev_b32_e32 v62, 16, v133
	v_and_b32_e32 v63, 0xffff0000, v133
	v_pk_mul_f32 v[62:63], v[62:63], v[44:45]
	v_pk_fma_f32 v[62:63], v[62:63], v[4:5], v[166:167]
	v_cvt_pk_bf16_f32 v133, v62, v63
	v_lshlrev_b32_e32 v64, 16, v134
	v_and_b32_e32 v65, 0xffff0000, v134
	v_pk_mul_f32 v[64:65], v[64:65], v[44:45]
	v_pk_fma_f32 v[64:65], v[64:65], v[6:7], v[168:169]
	v_cvt_pk_bf16_f32 v134, v64, v65
	v_lshlrev_b32_e32 v66, 16, v135
	v_and_b32_e32 v67, 0xffff0000, v135
	v_pk_mul_f32 v[66:67], v[66:67], v[44:45]
	v_pk_fma_f32 v[66:67], v[66:67], v[8:9], v[170:171]
	v_cvt_pk_bf16_f32 v135, v66, v67
	v_lshlrev_b32_e32 v60, 16, v136
	v_and_b32_e32 v61, 0xffff0000, v136
	v_pk_mul_f32 v[60:61], v[60:61], v[44:45]
	v_pk_fma_f32 v[60:61], v[60:61], v[10:11], v[172:173]
	v_cvt_pk_bf16_f32 v136, v60, v61
	v_lshlrev_b32_e32 v62, 16, v137
	v_and_b32_e32 v63, 0xffff0000, v137
	v_pk_mul_f32 v[62:63], v[62:63], v[44:45]
	v_pk_fma_f32 v[62:63], v[62:63], v[12:13], v[174:175]
	v_cvt_pk_bf16_f32 v137, v62, v63
	v_lshlrev_b32_e32 v64, 16, v138
	v_and_b32_e32 v65, 0xffff0000, v138
	v_pk_mul_f32 v[64:65], v[64:65], v[44:45]
	v_pk_fma_f32 v[64:65], v[64:65], v[14:15], v[176:177]
	v_cvt_pk_bf16_f32 v138, v64, v65
	v_lshlrev_b32_e32 v66, 16, v139
	v_and_b32_e32 v67, 0xffff0000, v139
	v_pk_mul_f32 v[66:67], v[66:67], v[44:45]
	v_pk_fma_f32 v[66:67], v[66:67], v[16:17], v[178:179]
	v_cvt_pk_bf16_f32 v139, v66, v67
	v_lshlrev_b32_e32 v60, 16, v140
	v_and_b32_e32 v61, 0xffff0000, v140
	v_pk_mul_f32 v[60:61], v[60:61], v[44:45]
	v_pk_fma_f32 v[60:61], v[60:61], v[18:19], v[180:181]
	v_cvt_pk_bf16_f32 v140, v60, v61
	v_lshlrev_b32_e32 v62, 16, v141
	v_and_b32_e32 v63, 0xffff0000, v141
	v_pk_mul_f32 v[62:63], v[62:63], v[44:45]
	v_pk_fma_f32 v[62:63], v[62:63], v[20:21], v[182:183]
	v_cvt_pk_bf16_f32 v141, v62, v63
	v_lshlrev_b32_e32 v64, 16, v142
	v_and_b32_e32 v65, 0xffff0000, v142
	v_pk_mul_f32 v[64:65], v[64:65], v[44:45]
	v_pk_fma_f32 v[64:65], v[64:65], v[22:23], v[184:185]
	v_cvt_pk_bf16_f32 v142, v64, v65
	v_lshlrev_b32_e32 v66, 16, v143
	v_and_b32_e32 v67, 0xffff0000, v143
	v_pk_mul_f32 v[66:67], v[66:67], v[44:45]
	v_pk_fma_f32 v[66:67], v[66:67], v[24:25], v[186:187]
	v_cvt_pk_bf16_f32 v143, v66, v67
	v_lshlrev_b32_e32 v60, 16, v144
	v_and_b32_e32 v61, 0xffff0000, v144
	v_pk_mul_f32 v[60:61], v[60:61], v[44:45]
	v_pk_fma_f32 v[60:61], v[60:61], v[26:27], v[188:189]
	v_cvt_pk_bf16_f32 v144, v60, v61
	v_lshlrev_b32_e32 v62, 16, v145
	v_and_b32_e32 v63, 0xffff0000, v145
	v_pk_mul_f32 v[62:63], v[62:63], v[44:45]
	v_pk_fma_f32 v[62:63], v[62:63], v[28:29], v[190:191]
	v_cvt_pk_bf16_f32 v145, v62, v63
	v_lshlrev_b32_e32 v64, 16, v146
	v_and_b32_e32 v65, 0xffff0000, v146
	v_pk_mul_f32 v[64:65], v[64:65], v[44:45]
	v_pk_fma_f32 v[64:65], v[64:65], v[30:31], v[192:193]
	v_cvt_pk_bf16_f32 v146, v64, v65
	v_lshlrev_b32_e32 v66, 16, v147
	v_and_b32_e32 v67, 0xffff0000, v147
	v_pk_mul_f32 v[66:67], v[66:67], v[44:45]
	v_pk_fma_f32 v[66:67], v[66:67], v[32:33], v[194:195]
	v_cvt_pk_bf16_f32 v147, v66, v67
	global_store_dwordx4 v39, v[132:135], s[20:21]
	global_store_dwordx4 v39, v[136:139], s[20:21] offset:1024
	global_store_dwordx4 v39, v[140:143], s[20:21] offset:2048
	global_store_dwordx4 v39, v[144:147], s[20:21] offset:3072
	s_add_u32 s20, s20, 0x1000
	s_addc_u32 s21, s21, 0
	global_load_dwordx4 v[132:135], v39, s[10:11]
	global_load_dwordx4 v[136:139], v39, s[10:11] offset:1024
	global_load_dwordx4 v[140:143], v39, s[10:11] offset:2048
	global_load_dwordx4 v[144:147], v39, s[10:11] offset:3072
	s_add_u32 s10, s10, 0x1000
	s_addc_u32 s11, s11, 0
	s_waitcnt vmcnt(24)
	v_lshlrev_b32_e32 v60, 16, v148
	v_and_b32_e32 v61, 0xffff0000, v148
	v_pk_mul_f32 v[42:43], v[60:61], v[60:61]
	v_lshlrev_b32_e32 v62, 16, v149
	v_and_b32_e32 v63, 0xffff0000, v149
	v_pk_fma_f32 v[42:43], v[62:63], v[62:63], v[42:43]
	v_lshlrev_b32_e32 v64, 16, v150
	v_and_b32_e32 v65, 0xffff0000, v150
	v_pk_fma_f32 v[42:43], v[64:65], v[64:65], v[42:43]
	v_lshlrev_b32_e32 v66, 16, v151
	v_and_b32_e32 v67, 0xffff0000, v151
	v_pk_fma_f32 v[42:43], v[66:67], v[66:67], v[42:43]
	v_lshlrev_b32_e32 v60, 16, v152
	v_and_b32_e32 v61, 0xffff0000, v152
	v_pk_fma_f32 v[42:43], v[60:61], v[60:61], v[42:43]
	v_lshlrev_b32_e32 v62, 16, v153
	v_and_b32_e32 v63, 0xffff0000, v153
	v_pk_fma_f32 v[42:43], v[62:63], v[62:63], v[42:43]
	v_lshlrev_b32_e32 v64, 16, v154
	v_and_b32_e32 v65, 0xffff0000, v154
	v_pk_fma_f32 v[42:43], v[64:65], v[64:65], v[42:43]
	v_lshlrev_b32_e32 v66, 16, v155
	v_and_b32_e32 v67, 0xffff0000, v155
	v_pk_fma_f32 v[42:43], v[66:67], v[66:67], v[42:43]
	v_lshlrev_b32_e32 v60, 16, v156
	v_and_b32_e32 v61, 0xffff0000, v156
	v_pk_fma_f32 v[42:43], v[60:61], v[60:61], v[42:43]
	v_lshlrev_b32_e32 v62, 16, v157
	v_and_b32_e32 v63, 0xffff0000, v157
	v_pk_fma_f32 v[42:43], v[62:63], v[62:63], v[42:43]
	v_lshlrev_b32_e32 v64, 16, v158
	v_and_b32_e32 v65, 0xffff0000, v158
	v_pk_fma_f32 v[42:43], v[64:65], v[64:65], v[42:43]
	v_lshlrev_b32_e32 v66, 16, v159
	v_and_b32_e32 v67, 0xffff0000, v159
	v_pk_fma_f32 v[42:43], v[66:67], v[66:67], v[42:43]
	v_lshlrev_b32_e32 v60, 16, v160
	v_and_b32_e32 v61, 0xffff0000, v160
	v_pk_fma_f32 v[42:43], v[60:61], v[60:61], v[42:43]
	v_lshlrev_b32_e32 v62, 16, v161
	v_and_b32_e32 v63, 0xffff0000, v161
	v_pk_fma_f32 v[42:43], v[62:63], v[62:63], v[42:43]
	v_lshlrev_b32_e32 v64, 16, v162
	v_and_b32_e32 v65, 0xffff0000, v162
	v_pk_fma_f32 v[42:43], v[64:65], v[64:65], v[42:43]
	v_lshlrev_b32_e32 v66, 16, v163
	v_and_b32_e32 v67, 0xffff0000, v163
	v_pk_fma_f32 v[42:43], v[66:67], v[66:67], v[42:43]
	v_add_f32_e32 v42, v42, v43
	s_nop 1
	v_add_f32_dpp v42, v42, v42 quad_perm:[1,0,3,2] row_mask:0xf bank_mask:0xf
	s_nop 1
	v_add_f32_dpp v42, v42, v42 quad_perm:[2,3,0,1] row_mask:0xf bank_mask:0xf
	s_nop 1
	v_add_f32_dpp v42, v42, v42 row_half_mirror row_mask:0xf bank_mask:0xf
	s_nop 1
	v_add_f32_dpp v42, v42, v42 row_mirror row_mask:0xf bank_mask:0xf
	s_nop 1
	v_add_f32_dpp v42, v42, v42 row_bcast:15 row_mask:0xa bank_mask:0xf
	s_nop 1
	v_add_f32_dpp v42, v42, v42 row_bcast:31 row_mask:0xc bank_mask:0xf
	s_nop 1
	v_readlane_b32 s100, v42, 63
	s_nop 3
	v_mov_b32_e32 v44, s100
	v_fma_f32 v44, v44, v47, v224
	v_rsq_f32_e32 v45, v44
	s_nop 0
	v_mul_f32_e32 v46, v44, v45
	v_mul_f32_e32 v46, v46, v45
	v_fmaak_f32 v46, -0.5, v46, 0x3fc00000
	v_mul_f32_e32 v44, v45, v46
	v_mov_b32_e32 v45, v44
	v_lshlrev_b32_e32 v60, 16, v148
	v_and_b32_e32 v61, 0xffff0000, v148
	v_pk_mul_f32 v[60:61], v[60:61], v[44:45]
	v_pk_fma_f32 v[60:61], v[60:61], v[2:3], v[164:165]
	v_cvt_pk_bf16_f32 v148, v60, v61
	v_lshlrev_b32_e32 v62, 16, v149
	v_and_b32_e32 v63, 0xffff0000, v149
	v_pk_mul_f32 v[62:63], v[62:63], v[44:45]
	v_pk_fma_f32 v[62:63], v[62:63], v[4:5], v[166:167]
	v_cvt_pk_bf16_f32 v149, v62, v63
	v_lshlrev_b32_e32 v64, 16, v150
	v_and_b32_e32 v65, 0xffff0000, v150
	v_pk_mul_f32 v[64:65], v[64:65], v[44:45]
	v_pk_fma_f32 v[64:65], v[64:65], v[6:7], v[168:169]
	v_cvt_pk_bf16_f32 v150, v64, v65
	v_lshlrev_b32_e32 v66, 16, v151
	v_and_b32_e32 v67, 0xffff0000, v151
	v_pk_mul_f32 v[66:67], v[66:67], v[44:45]
	v_pk_fma_f32 v[66:67], v[66:67], v[8:9], v[170:171]
	v_cvt_pk_bf16_f32 v151, v66, v67
	v_lshlrev_b32_e32 v60, 16, v152
	v_and_b32_e32 v61, 0xffff0000, v152
	v_pk_mul_f32 v[60:61], v[60:61], v[44:45]
	v_pk_fma_f32 v[60:61], v[60:61], v[10:11], v[172:173]
	v_cvt_pk_bf16_f32 v152, v60, v61
	v_lshlrev_b32_e32 v62, 16, v153
	v_and_b32_e32 v63, 0xffff0000, v153
	v_pk_mul_f32 v[62:63], v[62:63], v[44:45]
	v_pk_fma_f32 v[62:63], v[62:63], v[12:13], v[174:175]
	v_cvt_pk_bf16_f32 v153, v62, v63
	v_lshlrev_b32_e32 v64, 16, v154
	v_and_b32_e32 v65, 0xffff0000, v154
	v_pk_mul_f32 v[64:65], v[64:65], v[44:45]
	v_pk_fma_f32 v[64:65], v[64:65], v[14:15], v[176:177]
	v_cvt_pk_bf16_f32 v154, v64, v65
	v_lshlrev_b32_e32 v66, 16, v155
	v_and_b32_e32 v67, 0xffff0000, v155
	v_pk_mul_f32 v[66:67], v[66:67], v[44:45]
	v_pk_fma_f32 v[66:67], v[66:67], v[16:17], v[178:179]
	v_cvt_pk_bf16_f32 v155, v66, v67
	v_lshlrev_b32_e32 v60, 16, v156
	v_and_b32_e32 v61, 0xffff0000, v156
	v_pk_mul_f32 v[60:61], v[60:61], v[44:45]
	v_pk_fma_f32 v[60:61], v[60:61], v[18:19], v[180:181]
	v_cvt_pk_bf16_f32 v156, v60, v61
	v_lshlrev_b32_e32 v62, 16, v157
	v_and_b32_e32 v63, 0xffff0000, v157
	v_pk_mul_f32 v[62:63], v[62:63], v[44:45]
	v_pk_fma_f32 v[62:63], v[62:63], v[20:21], v[182:183]
	v_cvt_pk_bf16_f32 v157, v62, v63
	v_lshlrev_b32_e32 v64, 16, v158
	v_and_b32_e32 v65, 0xffff0000, v158
	v_pk_mul_f32 v[64:65], v[64:65], v[44:45]
	v_pk_fma_f32 v[64:65], v[64:65], v[22:23], v[184:185]
	v_cvt_pk_bf16_f32 v158, v64, v65
	v_lshlrev_b32_e32 v66, 16, v159
	v_and_b32_e32 v67, 0xffff0000, v159
	v_pk_mul_f32 v[66:67], v[66:67], v[44:45]
	v_pk_fma_f32 v[66:67], v[66:67], v[24:25], v[186:187]
	v_cvt_pk_bf16_f32 v159, v66, v67
	v_lshlrev_b32_e32 v60, 16, v160
	v_and_b32_e32 v61, 0xffff0000, v160
	v_pk_mul_f32 v[60:61], v[60:61], v[44:45]
	v_pk_fma_f32 v[60:61], v[60:61], v[26:27], v[188:189]
	v_cvt_pk_bf16_f32 v160, v60, v61
	v_lshlrev_b32_e32 v62, 16, v161
	v_and_b32_e32 v63, 0xffff0000, v161
	v_pk_mul_f32 v[62:63], v[62:63], v[44:45]
	v_pk_fma_f32 v[62:63], v[62:63], v[28:29], v[190:191]
	v_cvt_pk_bf16_f32 v161, v62, v63
	v_lshlrev_b32_e32 v64, 16, v162
	v_and_b32_e32 v65, 0xffff0000, v162
	v_pk_mul_f32 v[64:65], v[64:65], v[44:45]
	v_pk_fma_f32 v[64:65], v[64:65], v[30:31], v[192:193]
	v_cvt_pk_bf16_f32 v162, v64, v65
	v_lshlrev_b32_e32 v66, 16, v163
	v_and_b32_e32 v67, 0xffff0000, v163
	v_pk_mul_f32 v[66:67], v[66:67], v[44:45]
	v_pk_fma_f32 v[66:67], v[66:67], v[32:33], v[194:195]
	v_cvt_pk_bf16_f32 v163, v66, v67
	global_store_dwordx4 v39, v[148:151], s[20:21]
	global_store_dwordx4 v39, v[152:155], s[20:21] offset:1024
	global_store_dwordx4 v39, v[156:159], s[20:21] offset:2048
	global_store_dwordx4 v39, v[160:163], s[20:21] offset:3072
	s_add_u32 s20, s20, 0x1000
	s_addc_u32 s21, s21, 0
	global_load_dwordx4 v[148:151], v39, s[10:11]
	global_load_dwordx4 v[152:155], v39, s[10:11] offset:1024
	global_load_dwordx4 v[156:159], v39, s[10:11] offset:2048
	global_load_dwordx4 v[160:163], v39, s[10:11] offset:3072
	s_add_u32 s10, s10, 0x1000
	s_addc_u32 s11, s11, 0
	s_waitcnt vmcnt(24)
	v_lshlrev_b32_e32 v60, 16, v100
	v_and_b32_e32 v61, 0xffff0000, v100
	v_pk_mul_f32 v[42:43], v[60:61], v[60:61]
	v_lshlrev_b32_e32 v62, 16, v101
	v_and_b32_e32 v63, 0xffff0000, v101
	v_pk_fma_f32 v[42:43], v[62:63], v[62:63], v[42:43]
	v_lshlrev_b32_e32 v64, 16, v102
	v_and_b32_e32 v65, 0xffff0000, v102
	v_pk_fma_f32 v[42:43], v[64:65], v[64:65], v[42:43]
	v_lshlrev_b32_e32 v66, 16, v103
	v_and_b32_e32 v67, 0xffff0000, v103
	v_pk_fma_f32 v[42:43], v[66:67], v[66:67], v[42:43]
	v_lshlrev_b32_e32 v60, 16, v104
	v_and_b32_e32 v61, 0xffff0000, v104
	v_pk_fma_f32 v[42:43], v[60:61], v[60:61], v[42:43]
	v_lshlrev_b32_e32 v62, 16, v105
	v_and_b32_e32 v63, 0xffff0000, v105
	v_pk_fma_f32 v[42:43], v[62:63], v[62:63], v[42:43]
	v_lshlrev_b32_e32 v64, 16, v106
	v_and_b32_e32 v65, 0xffff0000, v106
	v_pk_fma_f32 v[42:43], v[64:65], v[64:65], v[42:43]
	v_lshlrev_b32_e32 v66, 16, v107
	v_and_b32_e32 v67, 0xffff0000, v107
	v_pk_fma_f32 v[42:43], v[66:67], v[66:67], v[42:43]
	v_lshlrev_b32_e32 v60, 16, v108
	v_and_b32_e32 v61, 0xffff0000, v108
	v_pk_fma_f32 v[42:43], v[60:61], v[60:61], v[42:43]
	v_lshlrev_b32_e32 v62, 16, v109
	v_and_b32_e32 v63, 0xffff0000, v109
	v_pk_fma_f32 v[42:43], v[62:63], v[62:63], v[42:43]
	v_lshlrev_b32_e32 v64, 16, v110
	v_and_b32_e32 v65, 0xffff0000, v110
	v_pk_fma_f32 v[42:43], v[64:65], v[64:65], v[42:43]
	v_lshlrev_b32_e32 v66, 16, v111
	v_and_b32_e32 v67, 0xffff0000, v111
	v_pk_fma_f32 v[42:43], v[66:67], v[66:67], v[42:43]
	v_lshlrev_b32_e32 v60, 16, v112
	v_and_b32_e32 v61, 0xffff0000, v112
	v_pk_fma_f32 v[42:43], v[60:61], v[60:61], v[42:43]
	v_lshlrev_b32_e32 v62, 16, v113
	v_and_b32_e32 v63, 0xffff0000, v113
	v_pk_fma_f32 v[42:43], v[62:63], v[62:63], v[42:43]
	v_lshlrev_b32_e32 v64, 16, v114
	v_and_b32_e32 v65, 0xffff0000, v114
	v_pk_fma_f32 v[42:43], v[64:65], v[64:65], v[42:43]
	v_lshlrev_b32_e32 v66, 16, v115
	v_and_b32_e32 v67, 0xffff0000, v115
	v_pk_fma_f32 v[42:43], v[66:67], v[66:67], v[42:43]
	v_add_f32_e32 v42, v42, v43
	s_nop 1
	v_add_f32_dpp v42, v42, v42 quad_perm:[1,0,3,2] row_mask:0xf bank_mask:0xf
	s_nop 1
	v_add_f32_dpp v42, v42, v42 quad_perm:[2,3,0,1] row_mask:0xf bank_mask:0xf
	s_nop 1
	v_add_f32_dpp v42, v42, v42 row_half_mirror row_mask:0xf bank_mask:0xf
	s_nop 1
	v_add_f32_dpp v42, v42, v42 row_mirror row_mask:0xf bank_mask:0xf
	s_nop 1
	v_add_f32_dpp v42, v42, v42 row_bcast:15 row_mask:0xa bank_mask:0xf
	s_nop 1
	v_add_f32_dpp v42, v42, v42 row_bcast:31 row_mask:0xc bank_mask:0xf
	s_nop 1
	v_readlane_b32 s100, v42, 63
	s_nop 3
	v_mov_b32_e32 v44, s100
	v_fma_f32 v44, v44, v47, v224
	v_rsq_f32_e32 v45, v44
	s_nop 0
	v_mul_f32_e32 v46, v44, v45
	v_mul_f32_e32 v46, v46, v45
	v_fmaak_f32 v46, -0.5, v46, 0x3fc00000
	v_mul_f32_e32 v44, v45, v46
	v_mov_b32_e32 v45, v44
	v_lshlrev_b32_e32 v60, 16, v100
	v_and_b32_e32 v61, 0xffff0000, v100
	v_pk_mul_f32 v[60:61], v[60:61], v[44:45]
	v_pk_fma_f32 v[60:61], v[60:61], v[2:3], v[164:165]
	v_cvt_pk_bf16_f32 v100, v60, v61
	v_lshlrev_b32_e32 v62, 16, v101
	v_and_b32_e32 v63, 0xffff0000, v101
	v_pk_mul_f32 v[62:63], v[62:63], v[44:45]
	v_pk_fma_f32 v[62:63], v[62:63], v[4:5], v[166:167]
	v_cvt_pk_bf16_f32 v101, v62, v63
	v_lshlrev_b32_e32 v64, 16, v102
	v_and_b32_e32 v65, 0xffff0000, v102
	v_pk_mul_f32 v[64:65], v[64:65], v[44:45]
	v_pk_fma_f32 v[64:65], v[64:65], v[6:7], v[168:169]
	v_cvt_pk_bf16_f32 v102, v64, v65
	v_lshlrev_b32_e32 v66, 16, v103
	v_and_b32_e32 v67, 0xffff0000, v103
	v_pk_mul_f32 v[66:67], v[66:67], v[44:45]
	v_pk_fma_f32 v[66:67], v[66:67], v[8:9], v[170:171]
	v_cvt_pk_bf16_f32 v103, v66, v67
	v_lshlrev_b32_e32 v60, 16, v104
	v_and_b32_e32 v61, 0xffff0000, v104
	v_pk_mul_f32 v[60:61], v[60:61], v[44:45]
	v_pk_fma_f32 v[60:61], v[60:61], v[10:11], v[172:173]
	v_cvt_pk_bf16_f32 v104, v60, v61
	v_lshlrev_b32_e32 v62, 16, v105
	v_and_b32_e32 v63, 0xffff0000, v105
	v_pk_mul_f32 v[62:63], v[62:63], v[44:45]
	v_pk_fma_f32 v[62:63], v[62:63], v[12:13], v[174:175]
	v_cvt_pk_bf16_f32 v105, v62, v63
	v_lshlrev_b32_e32 v64, 16, v106
	v_and_b32_e32 v65, 0xffff0000, v106
	v_pk_mul_f32 v[64:65], v[64:65], v[44:45]
	v_pk_fma_f32 v[64:65], v[64:65], v[14:15], v[176:177]
	v_cvt_pk_bf16_f32 v106, v64, v65
	v_lshlrev_b32_e32 v66, 16, v107
	v_and_b32_e32 v67, 0xffff0000, v107
	v_pk_mul_f32 v[66:67], v[66:67], v[44:45]
	v_pk_fma_f32 v[66:67], v[66:67], v[16:17], v[178:179]
	v_cvt_pk_bf16_f32 v107, v66, v67
	v_lshlrev_b32_e32 v60, 16, v108
	v_and_b32_e32 v61, 0xffff0000, v108
	v_pk_mul_f32 v[60:61], v[60:61], v[44:45]
	v_pk_fma_f32 v[60:61], v[60:61], v[18:19], v[180:181]
	v_cvt_pk_bf16_f32 v108, v60, v61
	v_lshlrev_b32_e32 v62, 16, v109
	v_and_b32_e32 v63, 0xffff0000, v109
	v_pk_mul_f32 v[62:63], v[62:63], v[44:45]
	v_pk_fma_f32 v[62:63], v[62:63], v[20:21], v[182:183]
	v_cvt_pk_bf16_f32 v109, v62, v63
	v_lshlrev_b32_e32 v64, 16, v110
	v_and_b32_e32 v65, 0xffff0000, v110
	v_pk_mul_f32 v[64:65], v[64:65], v[44:45]
	v_pk_fma_f32 v[64:65], v[64:65], v[22:23], v[184:185]
	v_cvt_pk_bf16_f32 v110, v64, v65
	v_lshlrev_b32_e32 v66, 16, v111
	v_and_b32_e32 v67, 0xffff0000, v111
	v_pk_mul_f32 v[66:67], v[66:67], v[44:45]
	v_pk_fma_f32 v[66:67], v[66:67], v[24:25], v[186:187]
	v_cvt_pk_bf16_f32 v111, v66, v67
	v_lshlrev_b32_e32 v60, 16, v112
	v_and_b32_e32 v61, 0xffff0000, v112
	v_pk_mul_f32 v[60:61], v[60:61], v[44:45]
	v_pk_fma_f32 v[60:61], v[60:61], v[26:27], v[188:189]
	v_cvt_pk_bf16_f32 v112, v60, v61
	v_lshlrev_b32_e32 v62, 16, v113
	v_and_b32_e32 v63, 0xffff0000, v113
	v_pk_mul_f32 v[62:63], v[62:63], v[44:45]
	v_pk_fma_f32 v[62:63], v[62:63], v[28:29], v[190:191]
	v_cvt_pk_bf16_f32 v113, v62, v63
	v_lshlrev_b32_e32 v64, 16, v114
	v_and_b32_e32 v65, 0xffff0000, v114
	v_pk_mul_f32 v[64:65], v[64:65], v[44:45]
	v_pk_fma_f32 v[64:65], v[64:65], v[30:31], v[192:193]
	v_cvt_pk_bf16_f32 v114, v64, v65
	v_lshlrev_b32_e32 v66, 16, v115
	v_and_b32_e32 v67, 0xffff0000, v115
	v_pk_mul_f32 v[66:67], v[66:67], v[44:45]
	v_pk_fma_f32 v[66:67], v[66:67], v[32:33], v[194:195]
	v_cvt_pk_bf16_f32 v115, v66, v67
	global_store_dwordx4 v39, v[100:103], s[20:21]
	global_store_dwordx4 v39, v[104:107], s[20:21] offset:1024
	global_store_dwordx4 v39, v[108:111], s[20:21] offset:2048
	global_store_dwordx4 v39, v[112:115], s[20:21] offset:3072
	s_add_u32 s20, s20, 0x1000
	s_addc_u32 s21, s21, 0
	s_waitcnt vmcnt(20)
	v_lshlrev_b32_e32 v60, 16, v116
	v_and_b32_e32 v61, 0xffff0000, v116
	v_pk_mul_f32 v[42:43], v[60:61], v[60:61]
	v_lshlrev_b32_e32 v62, 16, v117
	v_and_b32_e32 v63, 0xffff0000, v117
	v_pk_fma_f32 v[42:43], v[62:63], v[62:63], v[42:43]
	v_lshlrev_b32_e32 v64, 16, v118
	v_and_b32_e32 v65, 0xffff0000, v118
	v_pk_fma_f32 v[42:43], v[64:65], v[64:65], v[42:43]
	v_lshlrev_b32_e32 v66, 16, v119
	v_and_b32_e32 v67, 0xffff0000, v119
	v_pk_fma_f32 v[42:43], v[66:67], v[66:67], v[42:43]
	v_lshlrev_b32_e32 v60, 16, v120
	v_and_b32_e32 v61, 0xffff0000, v120
	v_pk_fma_f32 v[42:43], v[60:61], v[60:61], v[42:43]
	v_lshlrev_b32_e32 v62, 16, v121
	v_and_b32_e32 v63, 0xffff0000, v121
	v_pk_fma_f32 v[42:43], v[62:63], v[62:63], v[42:43]
	v_lshlrev_b32_e32 v64, 16, v122
	v_and_b32_e32 v65, 0xffff0000, v122
	v_pk_fma_f32 v[42:43], v[64:65], v[64:65], v[42:43]
	v_lshlrev_b32_e32 v66, 16, v123
	v_and_b32_e32 v67, 0xffff0000, v123
	v_pk_fma_f32 v[42:43], v[66:67], v[66:67], v[42:43]
	v_lshlrev_b32_e32 v60, 16, v124
	v_and_b32_e32 v61, 0xffff0000, v124
	v_pk_fma_f32 v[42:43], v[60:61], v[60:61], v[42:43]
	v_lshlrev_b32_e32 v62, 16, v125
	v_and_b32_e32 v63, 0xffff0000, v125
	v_pk_fma_f32 v[42:43], v[62:63], v[62:63], v[42:43]
	v_lshlrev_b32_e32 v64, 16, v126
	v_and_b32_e32 v65, 0xffff0000, v126
	v_pk_fma_f32 v[42:43], v[64:65], v[64:65], v[42:43]
	v_lshlrev_b32_e32 v66, 16, v127
	v_and_b32_e32 v67, 0xffff0000, v127
	v_pk_fma_f32 v[42:43], v[66:67], v[66:67], v[42:43]
	v_lshlrev_b32_e32 v60, 16, v128
	v_and_b32_e32 v61, 0xffff0000, v128
	v_pk_fma_f32 v[42:43], v[60:61], v[60:61], v[42:43]
	v_lshlrev_b32_e32 v62, 16, v129
	v_and_b32_e32 v63, 0xffff0000, v129
	v_pk_fma_f32 v[42:43], v[62:63], v[62:63], v[42:43]
	v_lshlrev_b32_e32 v64, 16, v130
	v_and_b32_e32 v65, 0xffff0000, v130
	v_pk_fma_f32 v[42:43], v[64:65], v[64:65], v[42:43]
	v_lshlrev_b32_e32 v66, 16, v131
	v_and_b32_e32 v67, 0xffff0000, v131
	v_pk_fma_f32 v[42:43], v[66:67], v[66:67], v[42:43]
	v_add_f32_e32 v42, v42, v43
	s_nop 1
	v_add_f32_dpp v42, v42, v42 quad_perm:[1,0,3,2] row_mask:0xf bank_mask:0xf
	s_nop 1
	v_add_f32_dpp v42, v42, v42 quad_perm:[2,3,0,1] row_mask:0xf bank_mask:0xf
	s_nop 1
	v_add_f32_dpp v42, v42, v42 row_half_mirror row_mask:0xf bank_mask:0xf
	s_nop 1
	v_add_f32_dpp v42, v42, v42 row_mirror row_mask:0xf bank_mask:0xf
	s_nop 1
	v_add_f32_dpp v42, v42, v42 row_bcast:15 row_mask:0xa bank_mask:0xf
	s_nop 1
	v_add_f32_dpp v42, v42, v42 row_bcast:31 row_mask:0xc bank_mask:0xf
	s_nop 1
	v_readlane_b32 s100, v42, 63
	s_nop 3
	v_mov_b32_e32 v44, s100
	v_fma_f32 v44, v44, v47, v224
	v_rsq_f32_e32 v45, v44
	s_nop 0
	v_mul_f32_e32 v46, v44, v45
	v_mul_f32_e32 v46, v46, v45
	v_fmaak_f32 v46, -0.5, v46, 0x3fc00000
	v_mul_f32_e32 v44, v45, v46
	v_mov_b32_e32 v45, v44
	v_lshlrev_b32_e32 v60, 16, v116
	v_and_b32_e32 v61, 0xffff0000, v116
	v_pk_mul_f32 v[60:61], v[60:61], v[44:45]
	v_pk_fma_f32 v[60:61], v[60:61], v[2:3], v[164:165]
	v_cvt_pk_bf16_f32 v116, v60, v61
	v_lshlrev_b32_e32 v62, 16, v117
	v_and_b32_e32 v63, 0xffff0000, v117
	v_pk_mul_f32 v[62:63], v[62:63], v[44:45]
	v_pk_fma_f32 v[62:63], v[62:63], v[4:5], v[166:167]
	v_cvt_pk_bf16_f32 v117, v62, v63
	v_lshlrev_b32_e32 v64, 16, v118
	v_and_b32_e32 v65, 0xffff0000, v118
	v_pk_mul_f32 v[64:65], v[64:65], v[44:45]
	v_pk_fma_f32 v[64:65], v[64:65], v[6:7], v[168:169]
	v_cvt_pk_bf16_f32 v118, v64, v65
	v_lshlrev_b32_e32 v66, 16, v119
	v_and_b32_e32 v67, 0xffff0000, v119
	v_pk_mul_f32 v[66:67], v[66:67], v[44:45]
	v_pk_fma_f32 v[66:67], v[66:67], v[8:9], v[170:171]
	v_cvt_pk_bf16_f32 v119, v66, v67
	v_lshlrev_b32_e32 v60, 16, v120
	v_and_b32_e32 v61, 0xffff0000, v120
	v_pk_mul_f32 v[60:61], v[60:61], v[44:45]
	v_pk_fma_f32 v[60:61], v[60:61], v[10:11], v[172:173]
	v_cvt_pk_bf16_f32 v120, v60, v61
	v_lshlrev_b32_e32 v62, 16, v121
	v_and_b32_e32 v63, 0xffff0000, v121
	v_pk_mul_f32 v[62:63], v[62:63], v[44:45]
	v_pk_fma_f32 v[62:63], v[62:63], v[12:13], v[174:175]
	v_cvt_pk_bf16_f32 v121, v62, v63
	v_lshlrev_b32_e32 v64, 16, v122
	v_and_b32_e32 v65, 0xffff0000, v122
	v_pk_mul_f32 v[64:65], v[64:65], v[44:45]
	v_pk_fma_f32 v[64:65], v[64:65], v[14:15], v[176:177]
	v_cvt_pk_bf16_f32 v122, v64, v65
	v_lshlrev_b32_e32 v66, 16, v123
	v_and_b32_e32 v67, 0xffff0000, v123
	v_pk_mul_f32 v[66:67], v[66:67], v[44:45]
	v_pk_fma_f32 v[66:67], v[66:67], v[16:17], v[178:179]
	v_cvt_pk_bf16_f32 v123, v66, v67
	v_lshlrev_b32_e32 v60, 16, v124
	v_and_b32_e32 v61, 0xffff0000, v124
	v_pk_mul_f32 v[60:61], v[60:61], v[44:45]
	v_pk_fma_f32 v[60:61], v[60:61], v[18:19], v[180:181]
	v_cvt_pk_bf16_f32 v124, v60, v61
	v_lshlrev_b32_e32 v62, 16, v125
	v_and_b32_e32 v63, 0xffff0000, v125
	v_pk_mul_f32 v[62:63], v[62:63], v[44:45]
	v_pk_fma_f32 v[62:63], v[62:63], v[20:21], v[182:183]
	v_cvt_pk_bf16_f32 v125, v62, v63
	v_lshlrev_b32_e32 v64, 16, v126
	v_and_b32_e32 v65, 0xffff0000, v126
	v_pk_mul_f32 v[64:65], v[64:65], v[44:45]
	v_pk_fma_f32 v[64:65], v[64:65], v[22:23], v[184:185]
	v_cvt_pk_bf16_f32 v126, v64, v65
	v_lshlrev_b32_e32 v66, 16, v127
	v_and_b32_e32 v67, 0xffff0000, v127
	v_pk_mul_f32 v[66:67], v[66:67], v[44:45]
	v_pk_fma_f32 v[66:67], v[66:67], v[24:25], v[186:187]
	v_cvt_pk_bf16_f32 v127, v66, v67
	v_lshlrev_b32_e32 v60, 16, v128
	v_and_b32_e32 v61, 0xffff0000, v128
	v_pk_mul_f32 v[60:61], v[60:61], v[44:45]
	v_pk_fma_f32 v[60:61], v[60:61], v[26:27], v[188:189]
	v_cvt_pk_bf16_f32 v128, v60, v61
	v_lshlrev_b32_e32 v62, 16, v129
	v_and_b32_e32 v63, 0xffff0000, v129
	v_pk_mul_f32 v[62:63], v[62:63], v[44:45]
	v_pk_fma_f32 v[62:63], v[62:63], v[28:29], v[190:191]
	v_cvt_pk_bf16_f32 v129, v62, v63
	v_lshlrev_b32_e32 v64, 16, v130
	v_and_b32_e32 v65, 0xffff0000, v130
	v_pk_mul_f32 v[64:65], v[64:65], v[44:45]
	v_pk_fma_f32 v[64:65], v[64:65], v[30:31], v[192:193]
	v_cvt_pk_bf16_f32 v130, v64, v65
	v_lshlrev_b32_e32 v66, 16, v131
	v_and_b32_e32 v67, 0xffff0000, v131
	v_pk_mul_f32 v[66:67], v[66:67], v[44:45]
	v_pk_fma_f32 v[66:67], v[66:67], v[32:33], v[194:195]
	v_cvt_pk_bf16_f32 v131, v66, v67
	global_store_dwordx4 v39, v[116:119], s[20:21]
	global_store_dwordx4 v39, v[120:123], s[20:21] offset:1024
	global_store_dwordx4 v39, v[124:127], s[20:21] offset:2048
	global_store_dwordx4 v39, v[128:131], s[20:21] offset:3072
	s_add_u32 s20, s20, 0x1000
	s_addc_u32 s21, s21, 0
	s_waitcnt vmcnt(16)
	v_lshlrev_b32_e32 v60, 16, v132
	v_and_b32_e32 v61, 0xffff0000, v132
	v_pk_mul_f32 v[42:43], v[60:61], v[60:61]
	v_lshlrev_b32_e32 v62, 16, v133
	v_and_b32_e32 v63, 0xffff0000, v133
	v_pk_fma_f32 v[42:43], v[62:63], v[62:63], v[42:43]
	v_lshlrev_b32_e32 v64, 16, v134
	v_and_b32_e32 v65, 0xffff0000, v134
	v_pk_fma_f32 v[42:43], v[64:65], v[64:65], v[42:43]
	v_lshlrev_b32_e32 v66, 16, v135
	v_and_b32_e32 v67, 0xffff0000, v135
	v_pk_fma_f32 v[42:43], v[66:67], v[66:67], v[42:43]
	v_lshlrev_b32_e32 v60, 16, v136
	v_and_b32_e32 v61, 0xffff0000, v136
	v_pk_fma_f32 v[42:43], v[60:61], v[60:61], v[42:43]
	v_lshlrev_b32_e32 v62, 16, v137
	v_and_b32_e32 v63, 0xffff0000, v137
	v_pk_fma_f32 v[42:43], v[62:63], v[62:63], v[42:43]
	v_lshlrev_b32_e32 v64, 16, v138
	v_and_b32_e32 v65, 0xffff0000, v138
	v_pk_fma_f32 v[42:43], v[64:65], v[64:65], v[42:43]
	v_lshlrev_b32_e32 v66, 16, v139
	v_and_b32_e32 v67, 0xffff0000, v139
	v_pk_fma_f32 v[42:43], v[66:67], v[66:67], v[42:43]
	v_lshlrev_b32_e32 v60, 16, v140
	v_and_b32_e32 v61, 0xffff0000, v140
	v_pk_fma_f32 v[42:43], v[60:61], v[60:61], v[42:43]
	v_lshlrev_b32_e32 v62, 16, v141
	v_and_b32_e32 v63, 0xffff0000, v141
	v_pk_fma_f32 v[42:43], v[62:63], v[62:63], v[42:43]
	v_lshlrev_b32_e32 v64, 16, v142
	v_and_b32_e32 v65, 0xffff0000, v142
	v_pk_fma_f32 v[42:43], v[64:65], v[64:65], v[42:43]
	v_lshlrev_b32_e32 v66, 16, v143
	v_and_b32_e32 v67, 0xffff0000, v143
	v_pk_fma_f32 v[42:43], v[66:67], v[66:67], v[42:43]
	v_lshlrev_b32_e32 v60, 16, v144
	v_and_b32_e32 v61, 0xffff0000, v144
	v_pk_fma_f32 v[42:43], v[60:61], v[60:61], v[42:43]
	v_lshlrev_b32_e32 v62, 16, v145
	v_and_b32_e32 v63, 0xffff0000, v145
	v_pk_fma_f32 v[42:43], v[62:63], v[62:63], v[42:43]
	v_lshlrev_b32_e32 v64, 16, v146
	v_and_b32_e32 v65, 0xffff0000, v146
	v_pk_fma_f32 v[42:43], v[64:65], v[64:65], v[42:43]
	v_lshlrev_b32_e32 v66, 16, v147
	v_and_b32_e32 v67, 0xffff0000, v147
	v_pk_fma_f32 v[42:43], v[66:67], v[66:67], v[42:43]
	v_add_f32_e32 v42, v42, v43
	s_nop 1
	v_add_f32_dpp v42, v42, v42 quad_perm:[1,0,3,2] row_mask:0xf bank_mask:0xf
	s_nop 1
	v_add_f32_dpp v42, v42, v42 quad_perm:[2,3,0,1] row_mask:0xf bank_mask:0xf
	s_nop 1
	v_add_f32_dpp v42, v42, v42 row_half_mirror row_mask:0xf bank_mask:0xf
	s_nop 1
	v_add_f32_dpp v42, v42, v42 row_mirror row_mask:0xf bank_mask:0xf
	s_nop 1
	v_add_f32_dpp v42, v42, v42 row_bcast:15 row_mask:0xa bank_mask:0xf
	s_nop 1
	v_add_f32_dpp v42, v42, v42 row_bcast:31 row_mask:0xc bank_mask:0xf
	s_nop 1
	v_readlane_b32 s100, v42, 63
	s_nop 3
	v_mov_b32_e32 v44, s100
	v_fma_f32 v44, v44, v47, v224
	v_rsq_f32_e32 v45, v44
	s_nop 0
	v_mul_f32_e32 v46, v44, v45
	v_mul_f32_e32 v46, v46, v45
	v_fmaak_f32 v46, -0.5, v46, 0x3fc00000
	v_mul_f32_e32 v44, v45, v46
	v_mov_b32_e32 v45, v44
	v_lshlrev_b32_e32 v60, 16, v132
	v_and_b32_e32 v61, 0xffff0000, v132
	v_pk_mul_f32 v[60:61], v[60:61], v[44:45]
	v_pk_fma_f32 v[60:61], v[60:61], v[2:3], v[164:165]
	v_cvt_pk_bf16_f32 v132, v60, v61
	v_lshlrev_b32_e32 v62, 16, v133
	v_and_b32_e32 v63, 0xffff0000, v133
	v_pk_mul_f32 v[62:63], v[62:63], v[44:45]
	v_pk_fma_f32 v[62:63], v[62:63], v[4:5], v[166:167]
	v_cvt_pk_bf16_f32 v133, v62, v63
	v_lshlrev_b32_e32 v64, 16, v134
	v_and_b32_e32 v65, 0xffff0000, v134
	v_pk_mul_f32 v[64:65], v[64:65], v[44:45]
	v_pk_fma_f32 v[64:65], v[64:65], v[6:7], v[168:169]
	v_cvt_pk_bf16_f32 v134, v64, v65
	v_lshlrev_b32_e32 v66, 16, v135
	v_and_b32_e32 v67, 0xffff0000, v135
	v_pk_mul_f32 v[66:67], v[66:67], v[44:45]
	v_pk_fma_f32 v[66:67], v[66:67], v[8:9], v[170:171]
	v_cvt_pk_bf16_f32 v135, v66, v67
	v_lshlrev_b32_e32 v60, 16, v136
	v_and_b32_e32 v61, 0xffff0000, v136
	v_pk_mul_f32 v[60:61], v[60:61], v[44:45]
	v_pk_fma_f32 v[60:61], v[60:61], v[10:11], v[172:173]
	v_cvt_pk_bf16_f32 v136, v60, v61
	v_lshlrev_b32_e32 v62, 16, v137
	v_and_b32_e32 v63, 0xffff0000, v137
	v_pk_mul_f32 v[62:63], v[62:63], v[44:45]
	v_pk_fma_f32 v[62:63], v[62:63], v[12:13], v[174:175]
	v_cvt_pk_bf16_f32 v137, v62, v63
	v_lshlrev_b32_e32 v64, 16, v138
	v_and_b32_e32 v65, 0xffff0000, v138
	v_pk_mul_f32 v[64:65], v[64:65], v[44:45]
	v_pk_fma_f32 v[64:65], v[64:65], v[14:15], v[176:177]
	v_cvt_pk_bf16_f32 v138, v64, v65
	v_lshlrev_b32_e32 v66, 16, v139
	v_and_b32_e32 v67, 0xffff0000, v139
	v_pk_mul_f32 v[66:67], v[66:67], v[44:45]
	v_pk_fma_f32 v[66:67], v[66:67], v[16:17], v[178:179]
	v_cvt_pk_bf16_f32 v139, v66, v67
	v_lshlrev_b32_e32 v60, 16, v140
	v_and_b32_e32 v61, 0xffff0000, v140
	v_pk_mul_f32 v[60:61], v[60:61], v[44:45]
	v_pk_fma_f32 v[60:61], v[60:61], v[18:19], v[180:181]
	v_cvt_pk_bf16_f32 v140, v60, v61
	v_lshlrev_b32_e32 v62, 16, v141
	v_and_b32_e32 v63, 0xffff0000, v141
	v_pk_mul_f32 v[62:63], v[62:63], v[44:45]
	v_pk_fma_f32 v[62:63], v[62:63], v[20:21], v[182:183]
	v_cvt_pk_bf16_f32 v141, v62, v63
	v_lshlrev_b32_e32 v64, 16, v142
	v_and_b32_e32 v65, 0xffff0000, v142
	v_pk_mul_f32 v[64:65], v[64:65], v[44:45]
	v_pk_fma_f32 v[64:65], v[64:65], v[22:23], v[184:185]
	v_cvt_pk_bf16_f32 v142, v64, v65
	v_lshlrev_b32_e32 v66, 16, v143
	v_and_b32_e32 v67, 0xffff0000, v143
	v_pk_mul_f32 v[66:67], v[66:67], v[44:45]
	v_pk_fma_f32 v[66:67], v[66:67], v[24:25], v[186:187]
	v_cvt_pk_bf16_f32 v143, v66, v67
	v_lshlrev_b32_e32 v60, 16, v144
	v_and_b32_e32 v61, 0xffff0000, v144
	v_pk_mul_f32 v[60:61], v[60:61], v[44:45]
	v_pk_fma_f32 v[60:61], v[60:61], v[26:27], v[188:189]
	v_cvt_pk_bf16_f32 v144, v60, v61
	v_lshlrev_b32_e32 v62, 16, v145
	v_and_b32_e32 v63, 0xffff0000, v145
	v_pk_mul_f32 v[62:63], v[62:63], v[44:45]
	v_pk_fma_f32 v[62:63], v[62:63], v[28:29], v[190:191]
	v_cvt_pk_bf16_f32 v145, v62, v63
	v_lshlrev_b32_e32 v64, 16, v146
	v_and_b32_e32 v65, 0xffff0000, v146
	v_pk_mul_f32 v[64:65], v[64:65], v[44:45]
	v_pk_fma_f32 v[64:65], v[64:65], v[30:31], v[192:193]
	v_cvt_pk_bf16_f32 v146, v64, v65
	v_lshlrev_b32_e32 v66, 16, v147
	v_and_b32_e32 v67, 0xffff0000, v147
	v_pk_mul_f32 v[66:67], v[66:67], v[44:45]
	v_pk_fma_f32 v[66:67], v[66:67], v[32:33], v[194:195]
	v_cvt_pk_bf16_f32 v147, v66, v67
	global_store_dwordx4 v39, v[132:135], s[20:21]
	global_store_dwordx4 v39, v[136:139], s[20:21] offset:1024
	global_store_dwordx4 v39, v[140:143], s[20:21] offset:2048
	global_store_dwordx4 v39, v[144:147], s[20:21] offset:3072
	s_add_u32 s20, s20, 0x1000
	s_addc_u32 s21, s21, 0
	s_waitcnt vmcnt(12)
	v_lshlrev_b32_e32 v60, 16, v148
	v_and_b32_e32 v61, 0xffff0000, v148
	v_pk_mul_f32 v[42:43], v[60:61], v[60:61]
	v_lshlrev_b32_e32 v62, 16, v149
	v_and_b32_e32 v63, 0xffff0000, v149
	v_pk_fma_f32 v[42:43], v[62:63], v[62:63], v[42:43]
	v_lshlrev_b32_e32 v64, 16, v150
	v_and_b32_e32 v65, 0xffff0000, v150
	v_pk_fma_f32 v[42:43], v[64:65], v[64:65], v[42:43]
	v_lshlrev_b32_e32 v66, 16, v151
	v_and_b32_e32 v67, 0xffff0000, v151
	v_pk_fma_f32 v[42:43], v[66:67], v[66:67], v[42:43]
	v_lshlrev_b32_e32 v60, 16, v152
	v_and_b32_e32 v61, 0xffff0000, v152
	v_pk_fma_f32 v[42:43], v[60:61], v[60:61], v[42:43]
	v_lshlrev_b32_e32 v62, 16, v153
	v_and_b32_e32 v63, 0xffff0000, v153
	v_pk_fma_f32 v[42:43], v[62:63], v[62:63], v[42:43]
	v_lshlrev_b32_e32 v64, 16, v154
	v_and_b32_e32 v65, 0xffff0000, v154
	v_pk_fma_f32 v[42:43], v[64:65], v[64:65], v[42:43]
	v_lshlrev_b32_e32 v66, 16, v155
	v_and_b32_e32 v67, 0xffff0000, v155
	v_pk_fma_f32 v[42:43], v[66:67], v[66:67], v[42:43]
	v_lshlrev_b32_e32 v60, 16, v156
	v_and_b32_e32 v61, 0xffff0000, v156
	v_pk_fma_f32 v[42:43], v[60:61], v[60:61], v[42:43]
	v_lshlrev_b32_e32 v62, 16, v157
	v_and_b32_e32 v63, 0xffff0000, v157
	v_pk_fma_f32 v[42:43], v[62:63], v[62:63], v[42:43]
	v_lshlrev_b32_e32 v64, 16, v158
	v_and_b32_e32 v65, 0xffff0000, v158
	v_pk_fma_f32 v[42:43], v[64:65], v[64:65], v[42:43]
	v_lshlrev_b32_e32 v66, 16, v159
	v_and_b32_e32 v67, 0xffff0000, v159
	v_pk_fma_f32 v[42:43], v[66:67], v[66:67], v[42:43]
	v_lshlrev_b32_e32 v60, 16, v160
	v_and_b32_e32 v61, 0xffff0000, v160
	v_pk_fma_f32 v[42:43], v[60:61], v[60:61], v[42:43]
	v_lshlrev_b32_e32 v62, 16, v161
	v_and_b32_e32 v63, 0xffff0000, v161
	v_pk_fma_f32 v[42:43], v[62:63], v[62:63], v[42:43]
	v_lshlrev_b32_e32 v64, 16, v162
	v_and_b32_e32 v65, 0xffff0000, v162
	v_pk_fma_f32 v[42:43], v[64:65], v[64:65], v[42:43]
	v_lshlrev_b32_e32 v66, 16, v163
	v_and_b32_e32 v67, 0xffff0000, v163
	v_pk_fma_f32 v[42:43], v[66:67], v[66:67], v[42:43]
	v_add_f32_e32 v42, v42, v43
	s_nop 1
	v_add_f32_dpp v42, v42, v42 quad_perm:[1,0,3,2] row_mask:0xf bank_mask:0xf
	s_nop 1
	v_add_f32_dpp v42, v42, v42 quad_perm:[2,3,0,1] row_mask:0xf bank_mask:0xf
	s_nop 1
	v_add_f32_dpp v42, v42, v42 row_half_mirror row_mask:0xf bank_mask:0xf
	s_nop 1
	v_add_f32_dpp v42, v42, v42 row_mirror row_mask:0xf bank_mask:0xf
	s_nop 1
	v_add_f32_dpp v42, v42, v42 row_bcast:15 row_mask:0xa bank_mask:0xf
	s_nop 1
	v_add_f32_dpp v42, v42, v42 row_bcast:31 row_mask:0xc bank_mask:0xf
	s_nop 1
	v_readlane_b32 s100, v42, 63
	s_nop 3
	v_mov_b32_e32 v44, s100
	v_fma_f32 v44, v44, v47, v224
	v_rsq_f32_e32 v45, v44
	s_nop 0
	v_mul_f32_e32 v46, v44, v45
	v_mul_f32_e32 v46, v46, v45
	v_fmaak_f32 v46, -0.5, v46, 0x3fc00000
	v_mul_f32_e32 v44, v45, v46
	v_mov_b32_e32 v45, v44
	v_lshlrev_b32_e32 v60, 16, v148
	v_and_b32_e32 v61, 0xffff0000, v148
	v_pk_mul_f32 v[60:61], v[60:61], v[44:45]
	v_pk_fma_f32 v[60:61], v[60:61], v[2:3], v[164:165]
	v_cvt_pk_bf16_f32 v148, v60, v61
	v_lshlrev_b32_e32 v62, 16, v149
	v_and_b32_e32 v63, 0xffff0000, v149
	v_pk_mul_f32 v[62:63], v[62:63], v[44:45]
	v_pk_fma_f32 v[62:63], v[62:63], v[4:5], v[166:167]
	v_cvt_pk_bf16_f32 v149, v62, v63
	v_lshlrev_b32_e32 v64, 16, v150
	v_and_b32_e32 v65, 0xffff0000, v150
	v_pk_mul_f32 v[64:65], v[64:65], v[44:45]
	v_pk_fma_f32 v[64:65], v[64:65], v[6:7], v[168:169]
	v_cvt_pk_bf16_f32 v150, v64, v65
	v_lshlrev_b32_e32 v66, 16, v151
	v_and_b32_e32 v67, 0xffff0000, v151
	v_pk_mul_f32 v[66:67], v[66:67], v[44:45]
	v_pk_fma_f32 v[66:67], v[66:67], v[8:9], v[170:171]
	v_cvt_pk_bf16_f32 v151, v66, v67
	v_lshlrev_b32_e32 v60, 16, v152
	v_and_b32_e32 v61, 0xffff0000, v152
	v_pk_mul_f32 v[60:61], v[60:61], v[44:45]
	v_pk_fma_f32 v[60:61], v[60:61], v[10:11], v[172:173]
	v_cvt_pk_bf16_f32 v152, v60, v61
	v_lshlrev_b32_e32 v62, 16, v153
	v_and_b32_e32 v63, 0xffff0000, v153
	v_pk_mul_f32 v[62:63], v[62:63], v[44:45]
	v_pk_fma_f32 v[62:63], v[62:63], v[12:13], v[174:175]
	v_cvt_pk_bf16_f32 v153, v62, v63
	v_lshlrev_b32_e32 v64, 16, v154
	v_and_b32_e32 v65, 0xffff0000, v154
	v_pk_mul_f32 v[64:65], v[64:65], v[44:45]
	v_pk_fma_f32 v[64:65], v[64:65], v[14:15], v[176:177]
	v_cvt_pk_bf16_f32 v154, v64, v65
	v_lshlrev_b32_e32 v66, 16, v155
	v_and_b32_e32 v67, 0xffff0000, v155
	v_pk_mul_f32 v[66:67], v[66:67], v[44:45]
	v_pk_fma_f32 v[66:67], v[66:67], v[16:17], v[178:179]
	v_cvt_pk_bf16_f32 v155, v66, v67
	v_lshlrev_b32_e32 v60, 16, v156
	v_and_b32_e32 v61, 0xffff0000, v156
	v_pk_mul_f32 v[60:61], v[60:61], v[44:45]
	v_pk_fma_f32 v[60:61], v[60:61], v[18:19], v[180:181]
	v_cvt_pk_bf16_f32 v156, v60, v61
	v_lshlrev_b32_e32 v62, 16, v157
	v_and_b32_e32 v63, 0xffff0000, v157
	v_pk_mul_f32 v[62:63], v[62:63], v[44:45]
	v_pk_fma_f32 v[62:63], v[62:63], v[20:21], v[182:183]
	v_cvt_pk_bf16_f32 v157, v62, v63
	v_lshlrev_b32_e32 v64, 16, v158
	v_and_b32_e32 v65, 0xffff0000, v158
	v_pk_mul_f32 v[64:65], v[64:65], v[44:45]
	v_pk_fma_f32 v[64:65], v[64:65], v[22:23], v[184:185]
	v_cvt_pk_bf16_f32 v158, v64, v65
	v_lshlrev_b32_e32 v66, 16, v159
	v_and_b32_e32 v67, 0xffff0000, v159
	v_pk_mul_f32 v[66:67], v[66:67], v[44:45]
	v_pk_fma_f32 v[66:67], v[66:67], v[24:25], v[186:187]
	v_cvt_pk_bf16_f32 v159, v66, v67
	v_lshlrev_b32_e32 v60, 16, v160
	v_and_b32_e32 v61, 0xffff0000, v160
	v_pk_mul_f32 v[60:61], v[60:61], v[44:45]
	v_pk_fma_f32 v[60:61], v[60:61], v[26:27], v[188:189]
	v_cvt_pk_bf16_f32 v160, v60, v61
	v_lshlrev_b32_e32 v62, 16, v161
	v_and_b32_e32 v63, 0xffff0000, v161
	v_pk_mul_f32 v[62:63], v[62:63], v[44:45]
	v_pk_fma_f32 v[62:63], v[62:63], v[28:29], v[190:191]
	v_cvt_pk_bf16_f32 v161, v62, v63
	v_lshlrev_b32_e32 v64, 16, v162
	v_and_b32_e32 v65, 0xffff0000, v162
	v_pk_mul_f32 v[64:65], v[64:65], v[44:45]
	v_pk_fma_f32 v[64:65], v[64:65], v[30:31], v[192:193]
	v_cvt_pk_bf16_f32 v162, v64, v65
	v_lshlrev_b32_e32 v66, 16, v163
	v_and_b32_e32 v67, 0xffff0000, v163
	v_pk_mul_f32 v[66:67], v[66:67], v[44:45]
	v_pk_fma_f32 v[66:67], v[66:67], v[32:33], v[194:195]
	v_cvt_pk_bf16_f32 v163, v66, v67
	global_store_dwordx4 v39, v[148:151], s[20:21]
	global_store_dwordx4 v39, v[152:155], s[20:21] offset:1024
	global_store_dwordx4 v39, v[156:159], s[20:21] offset:2048
	global_store_dwordx4 v39, v[160:163], s[20:21] offset:3072
	s_add_u32 s20, s20, 0x1000
	s_addc_u32 s21, s21, 0
.Lnf1_skip:
	s_branch .LBB0_225

.LBB0_225:
	s_cmp_eq_u32 s101, 0
	s_cbranch_scc1 .Lnf1_orig
	s_cmpk_lt_i32 s7, 0x4000
	s_cbranch_scc0 .Lnf1_orig
	s_add_i32 s7, s7, s36
	s_add_u32 s42, s42, s44
	s_addc_u32 s43, s43, s45
	v_lshl_add_u64 v[36:37], v[36:37], 0, s[38:39]
	s_cmpk_lt_i32 s7, 0x4400
	s_cbranch_scc1 .LBB0_225
	s_branch .LBB0_235

.LBB0_898:
	s_andn2_b64 vcc, exec, s[4:5]
	s_cbranch_vccnz .LBB0_962
	v_readlane_b32 s8, v253, 2
	s_mov_b64 s[4:5], s[96:97]
	s_mov_b64 s[36:37], s[96:97]
	s_mov_b64 s[20:21], s[96:97]
	v_mov_b32_e32 v2, v0
	v_readlane_b32 s9, v253, 3
	s_load_dword s6, s[8:9], 0x0
	v_readfirstlane_b32 s7, v2
	s_ashr_i32 s10, s7, 6
	v_readlane_b32 s7, v254, 16
	s_add_i32 s7, s10, s7
	s_cmp_ge_i32 s7, s81
	s_cbranch_scc1 .LBB0_908
	s_load_dwordx2 s[8:9], s[36:37], 0xb8
	s_waitcnt lgkmcnt(0)
	s_mul_i32 s52, s80, 0x5000
	s_lshl_b64 s[36:37], s[52:53], 2
	s_load_dwordx2 s[20:21], s[20:21], 0xb8
	s_mul_i32 s52, s80, 0xf000
	s_add_u32 s8, s8, s36
	s_addc_u32 s9, s9, s37
	s_add_u32 s8, s8, 0x195de000
	s_addc_u32 s9, s9, 0
	s_cmp_lg_u32 s80, 3
	s_cselect_b64 s[36:37], -1, 0
	s_cmp_eq_u32 s80, 0
	s_load_dwordx2 s[40:41], s[4:5], 0xb8
	s_cselect_b64 s[38:39], -1, 0
	s_lshl_b32 s42, s6, 3
	s_lshl_b64 s[44:45], s[52:53], 2
	s_waitcnt lgkmcnt(0)
	s_add_u32 s11, s20, s44
	s_addc_u32 s12, s21, s45
	v_and_b32_e32 v3, 63, v2
	s_add_u32 s54, s11, 0x194e6000
	v_lshlrev_b32_e32 v98, 5, v3
	s_addc_u32 s55, s12, 0
	v_lshl_add_u64 v[4:5], s[40:41], 0, v[98:99]
	s_mov_b64 s[12:13], 0x3bce8000
	v_lshl_add_u64 v[34:35], v[4:5], 0, s[12:13]
	s_ashr_i32 s11, s10, 31
	v_readlane_b32 s12, v254, 16
	s_add_u32 s10, s12, s10
	v_readlane_b32 s12, v254, 58
	s_addc_u32 s11, s12, s11
	s_lshl_b64 s[10:11], s[10:11], 12
	s_add_u32 s10, s40, s10
	v_lshlrev_b32_e32 v4, 3, v3
	v_lshlrev_b32_e32 v98, 4, v3
	s_addc_u32 s11, s41, s11
	v_lshlrev_b32_e32 v2, 1, v3
	v_or_b32_e32 v6, 0x400, v4
	v_or_b32_e32 v8, 0x600, v4
	v_lshl_add_u64 v[10:11], s[10:11], 0, v[98:99]
	s_mov_b64 s[10:11], 0x1da24c00
	s_ashr_i32 s43, s42, 31
	v_lshl_add_u64 v[36:37], v[10:11], 0, s[10:11]
	s_lshl_b64 s[44:45], s[42:43], 12
	v_lshlrev_b32_e32 v98, 4, v2
	v_lshlrev_b32_e32 v48, 2, v4
	v_lshlrev_b32_e32 v49, 2, v6
	v_lshlrev_b32_e32 v50, 2, v8
	s_mov_b32 s101, 0
	s_cmp_lg_u32 s6, 0x100
	s_cbranch_scc1 .Lnf2_skip
	s_mov_b32 s101, 1
	s_load_dwordx2 s[40:41], s[4:5], 0xb8
	v_and_b32_e32 v38, 63, v0
	v_lshlrev_b32_e32 v39, 4, v38
	v_lshlrev_b32_e32 v40, 5, v38
	s_lshl_b32 s10, s7, 15
	s_lshr_b32 s48, s7, 9
	s_lshl_b32 s20, s48, 13
	s_mul_i32 s49, s48, 0xc000
	s_waitcnt lgkmcnt(0)
	s_add_u32 s10, s40, s10
	s_addc_u32 s11, s41, 0
	s_add_u32 s10, s10, 0x19624000
	s_addc_u32 s11, s11, 0
	s_add_u32 s40, s8, s20
	s_addc_u32 s41, s9, 0
	s_add_u32 s48, s54, s49
	s_addc_u32 s49, s55, 0
	s_add_u32 s20, s10, 0x4400000
	s_addc_u32 s21, s11, 0
	global_load_dwordx4 v[100:103], v39, s[10:11]
	global_load_dwordx4 v[104:107], v39, s[10:11] offset:1024
	global_load_dwordx4 v[108:111], v39, s[10:11] offset:2048
	global_load_dwordx4 v[112:115], v39, s[10:11] offset:3072
	s_add_u32 s10, s10, 0x1000
	s_addc_u32 s11, s11, 0
	global_load_dwordx4 v[2:5], v40, s[40:41]
	global_load_dwordx4 v[6:9], v40, s[40:41] offset:16
	global_load_dwordx4 v[10:13], v40, s[40:41] offset:2048
	global_load_dwordx4 v[14:17], v40, s[40:41] offset:2064
	s_add_u32 s40, s40, 0x1000
	s_addc_u32 s41, s41, 0
	global_load_dwordx4 v[18:21], v40, s[40:41]
	global_load_dwordx4 v[22:25], v40, s[40:41] offset:16
	global_load_dwordx4 v[26:29], v40, s[40:41] offset:2048
	global_load_dwordx4 v[30:33], v40, s[40:41] offset:2064
	global_load_dwordx4 v[164:167], v40, s[48:49]
	global_load_dwordx4 v[168:171], v40, s[48:49] offset:16
	global_load_dwordx4 v[172:175], v40, s[48:49] offset:2048
	global_load_dwordx4 v[176:179], v40, s[48:49] offset:2064
	s_add_u32 s48, s48, 0x1000
	s_addc_u32 s49, s49, 0
	global_load_dwordx4 v[180:183], v40, s[48:49]
	global_load_dwordx4 v[184:187], v40, s[48:49] offset:16
	global_load_dwordx4 v[188:191], v40, s[48:49] offset:2048
	global_load_dwordx4 v[192:195], v40, s[48:49] offset:2064
	global_load_dwordx4 v[116:119], v39, s[10:11]
	global_load_dwordx4 v[120:123], v39, s[10:11] offset:1024
	global_load_dwordx4 v[124:127], v39, s[10:11] offset:2048
	global_load_dwordx4 v[128:131], v39, s[10:11] offset:3072
	s_add_u32 s10, s10, 0x1000
	s_addc_u32 s11, s11, 0
	global_load_dwordx4 v[132:135], v39, s[10:11]
	global_load_dwordx4 v[136:139], v39, s[10:11] offset:1024
	global_load_dwordx4 v[140:143], v39, s[10:11] offset:2048
	global_load_dwordx4 v[144:147], v39, s[10:11] offset:3072
	s_add_u32 s10, s10, 0x1000
	s_addc_u32 s11, s11, 0
	global_load_dwordx4 v[148:151], v39, s[10:11]
	global_load_dwordx4 v[152:155], v39, s[10:11] offset:1024
	global_load_dwordx4 v[156:159], v39, s[10:11] offset:2048
	global_load_dwordx4 v[160:163], v39, s[10:11] offset:3072
	s_add_u32 s10, s10, 0x1000
	s_addc_u32 s11, s11, 0
	v_mov_b32_e32 v47, 0x3a000000
	s_waitcnt vmcnt(28)
	v_lshlrev_b32_e32 v60, 16, v100
	v_and_b32_e32 v61, 0xffff0000, v100
	v_pk_mul_f32 v[42:43], v[60:61], v[60:61]
	v_lshlrev_b32_e32 v62, 16, v101
	v_and_b32_e32 v63, 0xffff0000, v101
	v_pk_fma_f32 v[42:43], v[62:63], v[62:63], v[42:43]
	v_lshlrev_b32_e32 v64, 16, v102
	v_and_b32_e32 v65, 0xffff0000, v102
	v_pk_fma_f32 v[42:43], v[64:65], v[64:65], v[42:43]
	v_lshlrev_b32_e32 v66, 16, v103
	v_and_b32_e32 v67, 0xffff0000, v103
	v_pk_fma_f32 v[42:43], v[66:67], v[66:67], v[42:43]
	v_lshlrev_b32_e32 v60, 16, v104
	v_and_b32_e32 v61, 0xffff0000, v104
	v_pk_fma_f32 v[42:43], v[60:61], v[60:61], v[42:43]
	v_lshlrev_b32_e32 v62, 16, v105
	v_and_b32_e32 v63, 0xffff0000, v105
	v_pk_fma_f32 v[42:43], v[62:63], v[62:63], v[42:43]
	v_lshlrev_b32_e32 v64, 16, v106
	v_and_b32_e32 v65, 0xffff0000, v106
	v_pk_fma_f32 v[42:43], v[64:65], v[64:65], v[42:43]
	v_lshlrev_b32_e32 v66, 16, v107
	v_and_b32_e32 v67, 0xffff0000, v107
	v_pk_fma_f32 v[42:43], v[66:67], v[66:67], v[42:43]
	v_lshlrev_b32_e32 v60, 16, v108
	v_and_b32_e32 v61, 0xffff0000, v108
	v_pk_fma_f32 v[42:43], v[60:61], v[60:61], v[42:43]
	v_lshlrev_b32_e32 v62, 16, v109
	v_and_b32_e32 v63, 0xffff0000, v109
	v_pk_fma_f32 v[42:43], v[62:63], v[62:63], v[42:43]
	v_lshlrev_b32_e32 v64, 16, v110
	v_and_b32_e32 v65, 0xffff0000, v110
	v_pk_fma_f32 v[42:43], v[64:65], v[64:65], v[42:43]
	v_lshlrev_b32_e32 v66, 16, v111
	v_and_b32_e32 v67, 0xffff0000, v111
	v_pk_fma_f32 v[42:43], v[66:67], v[66:67], v[42:43]
	v_lshlrev_b32_e32 v60, 16, v112
	v_and_b32_e32 v61, 0xffff0000, v112
	v_pk_fma_f32 v[42:43], v[60:61], v[60:61], v[42:43]
	v_lshlrev_b32_e32 v62, 16, v113
	v_and_b32_e32 v63, 0xffff0000, v113
	v_pk_fma_f32 v[42:43], v[62:63], v[62:63], v[42:43]
	v_lshlrev_b32_e32 v64, 16, v114
	v_and_b32_e32 v65, 0xffff0000, v114
	v_pk_fma_f32 v[42:43], v[64:65], v[64:65], v[42:43]
	v_lshlrev_b32_e32 v66, 16, v115
	v_and_b32_e32 v67, 0xffff0000, v115
	v_pk_fma_f32 v[42:43], v[66:67], v[66:67], v[42:43]
	v_add_f32_e32 v42, v42, v43
	s_nop 1
	v_add_f32_dpp v42, v42, v42 quad_perm:[1,0,3,2] row_mask:0xf bank_mask:0xf
	s_nop 1
	v_add_f32_dpp v42, v42, v42 quad_perm:[2,3,0,1] row_mask:0xf bank_mask:0xf
	s_nop 1
	v_add_f32_dpp v42, v42, v42 row_half_mirror row_mask:0xf bank_mask:0xf
	s_nop 1
	v_add_f32_dpp v42, v42, v42 row_mirror row_mask:0xf bank_mask:0xf
	s_nop 1
	v_add_f32_dpp v42, v42, v42 row_bcast:15 row_mask:0xa bank_mask:0xf
	s_nop 1
	v_add_f32_dpp v42, v42, v42 row_bcast:31 row_mask:0xc bank_mask:0xf
	s_nop 1
	v_readlane_b32 s100, v42, 63
	s_nop 3
	v_mov_b32_e32 v44, s100
	v_fma_f32 v44, v44, v47, v224
	v_rsq_f32_e32 v45, v44
	s_nop 0
	v_mul_f32_e32 v46, v44, v45
	v_mul_f32_e32 v46, v46, v45
	v_fmaak_f32 v46, -0.5, v46, 0x3fc00000
	v_mul_f32_e32 v44, v45, v46
	v_mov_b32_e32 v45, v44
	s_waitcnt vmcnt(12)
	v_lshlrev_b32_e32 v60, 16, v100
	v_and_b32_e32 v61, 0xffff0000, v100
	v_pk_mul_f32 v[60:61], v[60:61], v[44:45]
	v_pk_fma_f32 v[60:61], v[60:61], v[2:3], v[164:165]
	v_cvt_pk_bf16_f32 v100, v60, v61
	v_lshlrev_b32_e32 v62, 16, v101
	v_and_b32_e32 v63, 0xffff0000, v101
	v_pk_mul_f32 v[62:63], v[62:63], v[44:45]
	v_pk_fma_f32 v[62:63], v[62:63], v[4:5], v[166:167]
	v_cvt_pk_bf16_f32 v101, v62, v63
	v_lshlrev_b32_e32 v64, 16, v102
	v_and_b32_e32 v65, 0xffff0000, v102
	v_pk_mul_f32 v[64:65], v[64:65], v[44:45]
	v_pk_fma_f32 v[64:65], v[64:65], v[6:7], v[168:169]
	v_cvt_pk_bf16_f32 v102, v64, v65
	v_lshlrev_b32_e32 v66, 16, v103
	v_and_b32_e32 v67, 0xffff0000, v103
	v_pk_mul_f32 v[66:67], v[66:67], v[44:45]
	v_pk_fma_f32 v[66:67], v[66:67], v[8:9], v[170:171]
	v_cvt_pk_bf16_f32 v103, v66, v67
	v_lshlrev_b32_e32 v60, 16, v104
	v_and_b32_e32 v61, 0xffff0000, v104
	v_pk_mul_f32 v[60:61], v[60:61], v[44:45]
	v_pk_fma_f32 v[60:61], v[60:61], v[10:11], v[172:173]
	v_cvt_pk_bf16_f32 v104, v60, v61
	v_lshlrev_b32_e32 v62, 16, v105
	v_and_b32_e32 v63, 0xffff0000, v105
	v_pk_mul_f32 v[62:63], v[62:63], v[44:45]
	v_pk_fma_f32 v[62:63], v[62:63], v[12:13], v[174:175]
	v_cvt_pk_bf16_f32 v105, v62, v63
	v_lshlrev_b32_e32 v64, 16, v106
	v_and_b32_e32 v65, 0xffff0000, v106
	v_pk_mul_f32 v[64:65], v[64:65], v[44:45]
	v_pk_fma_f32 v[64:65], v[64:65], v[14:15], v[176:177]
	v_cvt_pk_bf16_f32 v106, v64, v65
	v_lshlrev_b32_e32 v66, 16, v107
	v_and_b32_e32 v67, 0xffff0000, v107
	v_pk_mul_f32 v[66:67], v[66:67], v[44:45]
	v_pk_fma_f32 v[66:67], v[66:67], v[16:17], v[178:179]
	v_cvt_pk_bf16_f32 v107, v66, v67
	v_lshlrev_b32_e32 v60, 16, v108
	v_and_b32_e32 v61, 0xffff0000, v108
	v_pk_mul_f32 v[60:61], v[60:61], v[44:45]
	v_pk_fma_f32 v[60:61], v[60:61], v[18:19], v[180:181]
	v_cvt_pk_bf16_f32 v108, v60, v61
	v_lshlrev_b32_e32 v62, 16, v109
	v_and_b32_e32 v63, 0xffff0000, v109
	v_pk_mul_f32 v[62:63], v[62:63], v[44:45]
	v_pk_fma_f32 v[62:63], v[62:63], v[20:21], v[182:183]
	v_cvt_pk_bf16_f32 v109, v62, v63
	v_lshlrev_b32_e32 v64, 16, v110
	v_and_b32_e32 v65, 0xffff0000, v110
	v_pk_mul_f32 v[64:65], v[64:65], v[44:45]
	v_pk_fma_f32 v[64:65], v[64:65], v[22:23], v[184:185]
	v_cvt_pk_bf16_f32 v110, v64, v65
	v_lshlrev_b32_e32 v66, 16, v111
	v_and_b32_e32 v67, 0xffff0000, v111
	v_pk_mul_f32 v[66:67], v[66:67], v[44:45]
	v_pk_fma_f32 v[66:67], v[66:67], v[24:25], v[186:187]
	v_cvt_pk_bf16_f32 v111, v66, v67
	v_lshlrev_b32_e32 v60, 16, v112
	v_and_b32_e32 v61, 0xffff0000, v112
	v_pk_mul_f32 v[60:61], v[60:61], v[44:45]
	v_pk_fma_f32 v[60:61], v[60:61], v[26:27], v[188:189]
	v_cvt_pk_bf16_f32 v112, v60, v61
	v_lshlrev_b32_e32 v62, 16, v113
	v_and_b32_e32 v63, 0xffff0000, v113
	v_pk_mul_f32 v[62:63], v[62:63], v[44:45]
	v_pk_fma_f32 v[62:63], v[62:63], v[28:29], v[190:191]
	v_cvt_pk_bf16_f32 v113, v62, v63
	v_lshlrev_b32_e32 v64, 16, v114
	v_and_b32_e32 v65, 0xffff0000, v114
	v_pk_mul_f32 v[64:65], v[64:65], v[44:45]
	v_pk_fma_f32 v[64:65], v[64:65], v[30:31], v[192:193]
	v_cvt_pk_bf16_f32 v114, v64, v65
	v_lshlrev_b32_e32 v66, 16, v115
	v_and_b32_e32 v67, 0xffff0000, v115
	v_pk_mul_f32 v[66:67], v[66:67], v[44:45]
	v_pk_fma_f32 v[66:67], v[66:67], v[32:33], v[194:195]
	v_cvt_pk_bf16_f32 v115, v66, v67
	global_store_dwordx4 v39, v[100:103], s[20:21]
	global_store_dwordx4 v39, v[104:107], s[20:21] offset:1024
	global_store_dwordx4 v39, v[108:111], s[20:21] offset:2048
	global_store_dwordx4 v39, v[112:115], s[20:21] offset:3072
	s_add_u32 s20, s20, 0x1000
	s_addc_u32 s21, s21, 0
	global_load_dwordx4 v[100:103], v39, s[10:11]
	global_load_dwordx4 v[104:107], v39, s[10:11] offset:1024
	global_load_dwordx4 v[108:111], v39, s[10:11] offset:2048
	global_load_dwordx4 v[112:115], v39, s[10:11] offset:3072
	s_add_u32 s10, s10, 0x1000
	s_addc_u32 s11, s11, 0
	s_waitcnt vmcnt(16)
	v_lshlrev_b32_e32 v60, 16, v116
	v_and_b32_e32 v61, 0xffff0000, v116
	v_pk_mul_f32 v[42:43], v[60:61], v[60:61]
	v_lshlrev_b32_e32 v62, 16, v117
	v_and_b32_e32 v63, 0xffff0000, v117
	v_pk_fma_f32 v[42:43], v[62:63], v[62:63], v[42:43]
	v_lshlrev_b32_e32 v64, 16, v118
	v_and_b32_e32 v65, 0xffff0000, v118
	v_pk_fma_f32 v[42:43], v[64:65], v[64:65], v[42:43]
	v_lshlrev_b32_e32 v66, 16, v119
	v_and_b32_e32 v67, 0xffff0000, v119
	v_pk_fma_f32 v[42:43], v[66:67], v[66:67], v[42:43]
	v_lshlrev_b32_e32 v60, 16, v120
	v_and_b32_e32 v61, 0xffff0000, v120
	v_pk_fma_f32 v[42:43], v[60:61], v[60:61], v[42:43]
	v_lshlrev_b32_e32 v62, 16, v121
	v_and_b32_e32 v63, 0xffff0000, v121
	v_pk_fma_f32 v[42:43], v[62:63], v[62:63], v[42:43]
	v_lshlrev_b32_e32 v64, 16, v122
	v_and_b32_e32 v65, 0xffff0000, v122
	v_pk_fma_f32 v[42:43], v[64:65], v[64:65], v[42:43]
	v_lshlrev_b32_e32 v66, 16, v123
	v_and_b32_e32 v67, 0xffff0000, v123
	v_pk_fma_f32 v[42:43], v[66:67], v[66:67], v[42:43]
	v_lshlrev_b32_e32 v60, 16, v124
	v_and_b32_e32 v61, 0xffff0000, v124
	v_pk_fma_f32 v[42:43], v[60:61], v[60:61], v[42:43]
	v_lshlrev_b32_e32 v62, 16, v125
	v_and_b32_e32 v63, 0xffff0000, v125
	v_pk_fma_f32 v[42:43], v[62:63], v[62:63], v[42:43]
	v_lshlrev_b32_e32 v64, 16, v126
	v_and_b32_e32 v65, 0xffff0000, v126
	v_pk_fma_f32 v[42:43], v[64:65], v[64:65], v[42:43]
	v_lshlrev_b32_e32 v66, 16, v127
	v_and_b32_e32 v67, 0xffff0000, v127
	v_pk_fma_f32 v[42:43], v[66:67], v[66:67], v[42:43]
	v_lshlrev_b32_e32 v60, 16, v128
	v_and_b32_e32 v61, 0xffff0000, v128
	v_pk_fma_f32 v[42:43], v[60:61], v[60:61], v[42:43]
	v_lshlrev_b32_e32 v62, 16, v129
	v_and_b32_e32 v63, 0xffff0000, v129
	v_pk_fma_f32 v[42:43], v[62:63], v[62:63], v[42:43]
	v_lshlrev_b32_e32 v64, 16, v130
	v_and_b32_e32 v65, 0xffff0000, v130
	v_pk_fma_f32 v[42:43], v[64:65], v[64:65], v[42:43]
	v_lshlrev_b32_e32 v66, 16, v131
	v_and_b32_e32 v67, 0xffff0000, v131
	v_pk_fma_f32 v[42:43], v[66:67], v[66:67], v[42:43]
	v_add_f32_e32 v42, v42, v43
	s_nop 1
	v_add_f32_dpp v42, v42, v42 quad_perm:[1,0,3,2] row_mask:0xf bank_mask:0xf
	s_nop 1
	v_add_f32_dpp v42, v42, v42 quad_perm:[2,3,0,1] row_mask:0xf bank_mask:0xf
	s_nop 1
	v_add_f32_dpp v42, v42, v42 row_half_mirror row_mask:0xf bank_mask:0xf
	s_nop 1
	v_add_f32_dpp v42, v42, v42 row_mirror row_mask:0xf bank_mask:0xf
	s_nop 1
	v_add_f32_dpp v42, v42, v42 row_bcast:15 row_mask:0xa bank_mask:0xf
	s_nop 1
	v_add_f32_dpp v42, v42, v42 row_bcast:31 row_mask:0xc bank_mask:0xf
	s_nop 1
	v_readlane_b32 s100, v42, 63
	s_nop 3
	v_mov_b32_e32 v44, s100
	v_fma_f32 v44, v44, v47, v224
	v_rsq_f32_e32 v45, v44
	s_nop 0
	v_mul_f32_e32 v46, v44, v45
	v_mul_f32_e32 v46, v46, v45
	v_fmaak_f32 v46, -0.5, v46, 0x3fc00000
	v_mul_f32_e32 v44, v45, v46
	v_mov_b32_e32 v45, v44
	v_lshlrev_b32_e32 v60, 16, v116
	v_and_b32_e32 v61, 0xffff0000, v116
	v_pk_mul_f32 v[60:61], v[60:61], v[44:45]
	v_pk_fma_f32 v[60:61], v[60:61], v[2:3], v[164:165]
	v_cvt_pk_bf16_f32 v116, v60, v61
	v_lshlrev_b32_e32 v62, 16, v117
	v_and_b32_e32 v63, 0xffff0000, v117
	v_pk_mul_f32 v[62:63], v[62:63], v[44:45]
	v_pk_fma_f32 v[62:63], v[62:63], v[4:5], v[166:167]
	v_cvt_pk_bf16_f32 v117, v62, v63
	v_lshlrev_b32_e32 v64, 16, v118
	v_and_b32_e32 v65, 0xffff0000, v118
	v_pk_mul_f32 v[64:65], v[64:65], v[44:45]
	v_pk_fma_f32 v[64:65], v[64:65], v[6:7], v[168:169]
	v_cvt_pk_bf16_f32 v118, v64, v65
	v_lshlrev_b32_e32 v66, 16, v119
	v_and_b32_e32 v67, 0xffff0000, v119
	v_pk_mul_f32 v[66:67], v[66:67], v[44:45]
	v_pk_fma_f32 v[66:67], v[66:67], v[8:9], v[170:171]
	v_cvt_pk_bf16_f32 v119, v66, v67
	v_lshlrev_b32_e32 v60, 16, v120
	v_and_b32_e32 v61, 0xffff0000, v120
	v_pk_mul_f32 v[60:61], v[60:61], v[44:45]
	v_pk_fma_f32 v[60:61], v[60:61], v[10:11], v[172:173]
	v_cvt_pk_bf16_f32 v120, v60, v61
	v_lshlrev_b32_e32 v62, 16, v121
	v_and_b32_e32 v63, 0xffff0000, v121
	v_pk_mul_f32 v[62:63], v[62:63], v[44:45]
	v_pk_fma_f32 v[62:63], v[62:63], v[12:13], v[174:175]
	v_cvt_pk_bf16_f32 v121, v62, v63
	v_lshlrev_b32_e32 v64, 16, v122
	v_and_b32_e32 v65, 0xffff0000, v122
	v_pk_mul_f32 v[64:65], v[64:65], v[44:45]
	v_pk_fma_f32 v[64:65], v[64:65], v[14:15], v[176:177]
	v_cvt_pk_bf16_f32 v122, v64, v65
	v_lshlrev_b32_e32 v66, 16, v123
	v_and_b32_e32 v67, 0xffff0000, v123
	v_pk_mul_f32 v[66:67], v[66:67], v[44:45]
	v_pk_fma_f32 v[66:67], v[66:67], v[16:17], v[178:179]
	v_cvt_pk_bf16_f32 v123, v66, v67
	v_lshlrev_b32_e32 v60, 16, v124
	v_and_b32_e32 v61, 0xffff0000, v124
	v_pk_mul_f32 v[60:61], v[60:61], v[44:45]
	v_pk_fma_f32 v[60:61], v[60:61], v[18:19], v[180:181]
	v_cvt_pk_bf16_f32 v124, v60, v61
	v_lshlrev_b32_e32 v62, 16, v125
	v_and_b32_e32 v63, 0xffff0000, v125
	v_pk_mul_f32 v[62:63], v[62:63], v[44:45]
	v_pk_fma_f32 v[62:63], v[62:63], v[20:21], v[182:183]
	v_cvt_pk_bf16_f32 v125, v62, v63
	v_lshlrev_b32_e32 v64, 16, v126
	v_and_b32_e32 v65, 0xffff0000, v126
	v_pk_mul_f32 v[64:65], v[64:65], v[44:45]
	v_pk_fma_f32 v[64:65], v[64:65], v[22:23], v[184:185]
	v_cvt_pk_bf16_f32 v126, v64, v65
	v_lshlrev_b32_e32 v66, 16, v127
	v_and_b32_e32 v67, 0xffff0000, v127
	v_pk_mul_f32 v[66:67], v[66:67], v[44:45]
	v_pk_fma_f32 v[66:67], v[66:67], v[24:25], v[186:187]
	v_cvt_pk_bf16_f32 v127, v66, v67
	v_lshlrev_b32_e32 v60, 16, v128
	v_and_b32_e32 v61, 0xffff0000, v128
	v_pk_mul_f32 v[60:61], v[60:61], v[44:45]
	v_pk_fma_f32 v[60:61], v[60:61], v[26:27], v[188:189]
	v_cvt_pk_bf16_f32 v128, v60, v61
	v_lshlrev_b32_e32 v62, 16, v129
	v_and_b32_e32 v63, 0xffff0000, v129
	v_pk_mul_f32 v[62:63], v[62:63], v[44:45]
	v_pk_fma_f32 v[62:63], v[62:63], v[28:29], v[190:191]
	v_cvt_pk_bf16_f32 v129, v62, v63
	v_lshlrev_b32_e32 v64, 16, v130
	v_and_b32_e32 v65, 0xffff0000, v130
	v_pk_mul_f32 v[64:65], v[64:65], v[44:45]
	v_pk_fma_f32 v[64:65], v[64:65], v[30:31], v[192:193]
	v_cvt_pk_bf16_f32 v130, v64, v65
	v_lshlrev_b32_e32 v66, 16, v131
	v_and_b32_e32 v67, 0xffff0000, v131
	v_pk_mul_f32 v[66:67], v[66:67], v[44:45]
	v_pk_fma_f32 v[66:67], v[66:67], v[32:33], v[194:195]
	v_cvt_pk_bf16_f32 v131, v66, v67
	global_store_dwordx4 v39, v[116:119], s[20:21]
	global_store_dwordx4 v39, v[120:123], s[20:21] offset:1024
	global_store_dwordx4 v39, v[124:127], s[20:21] offset:2048
	global_store_dwordx4 v39, v[128:131], s[20:21] offset:3072
	s_add_u32 s20, s20, 0x1000
	s_addc_u32 s21, s21, 0
	global_load_dwordx4 v[116:119], v39, s[10:11]
	global_load_dwordx4 v[120:123], v39, s[10:11] offset:1024
	global_load_dwordx4 v[124:127], v39, s[10:11] offset:2048
	global_load_dwordx4 v[128:131], v39, s[10:11] offset:3072
	s_add_u32 s10, s10, 0x1000
	s_addc_u32 s11, s11, 0
	s_waitcnt vmcnt(20)
	v_lshlrev_b32_e32 v60, 16, v132
	v_and_b32_e32 v61, 0xffff0000, v132
	v_pk_mul_f32 v[42:43], v[60:61], v[60:61]
	v_lshlrev_b32_e32 v62, 16, v133
	v_and_b32_e32 v63, 0xffff0000, v133
	v_pk_fma_f32 v[42:43], v[62:63], v[62:63], v[42:43]
	v_lshlrev_b32_e32 v64, 16, v134
	v_and_b32_e32 v65, 0xffff0000, v134
	v_pk_fma_f32 v[42:43], v[64:65], v[64:65], v[42:43]
	v_lshlrev_b32_e32 v66, 16, v135
	v_and_b32_e32 v67, 0xffff0000, v135
	v_pk_fma_f32 v[42:43], v[66:67], v[66:67], v[42:43]
	v_lshlrev_b32_e32 v60, 16, v136
	v_and_b32_e32 v61, 0xffff0000, v136
	v_pk_fma_f32 v[42:43], v[60:61], v[60:61], v[42:43]
	v_lshlrev_b32_e32 v62, 16, v137
	v_and_b32_e32 v63, 0xffff0000, v137
	v_pk_fma_f32 v[42:43], v[62:63], v[62:63], v[42:43]
	v_lshlrev_b32_e32 v64, 16, v138
	v_and_b32_e32 v65, 0xffff0000, v138
	v_pk_fma_f32 v[42:43], v[64:65], v[64:65], v[42:43]
	v_lshlrev_b32_e32 v66, 16, v139
	v_and_b32_e32 v67, 0xffff0000, v139
	v_pk_fma_f32 v[42:43], v[66:67], v[66:67], v[42:43]
	v_lshlrev_b32_e32 v60, 16, v140
	v_and_b32_e32 v61, 0xffff0000, v140
	v_pk_fma_f32 v[42:43], v[60:61], v[60:61], v[42:43]
	v_lshlrev_b32_e32 v62, 16, v141
	v_and_b32_e32 v63, 0xffff0000, v141
	v_pk_fma_f32 v[42:43], v[62:63], v[62:63], v[42:43]
	v_lshlrev_b32_e32 v64, 16, v142
	v_and_b32_e32 v65, 0xffff0000, v142
	v_pk_fma_f32 v[42:43], v[64:65], v[64:65], v[42:43]
	v_lshlrev_b32_e32 v66, 16, v143
	v_and_b32_e32 v67, 0xffff0000, v143
	v_pk_fma_f32 v[42:43], v[66:67], v[66:67], v[42:43]
	v_lshlrev_b32_e32 v60, 16, v144
	v_and_b32_e32 v61, 0xffff0000, v144
	v_pk_fma_f32 v[42:43], v[60:61], v[60:61], v[42:43]
	v_lshlrev_b32_e32 v62, 16, v145
	v_and_b32_e32 v63, 0xffff0000, v145
	v_pk_fma_f32 v[42:43], v[62:63], v[62:63], v[42:43]
	v_lshlrev_b32_e32 v64, 16, v146
	v_and_b32_e32 v65, 0xffff0000, v146
	v_pk_fma_f32 v[42:43], v[64:65], v[64:65], v[42:43]
	v_lshlrev_b32_e32 v66, 16, v147
	v_and_b32_e32 v67, 0xffff0000, v147
	v_pk_fma_f32 v[42:43], v[66:67], v[66:67], v[42:43]
	v_add_f32_e32 v42, v42, v43
	s_nop 1
	v_add_f32_dpp v42, v42, v42 quad_perm:[1,0,3,2] row_mask:0xf bank_mask:0xf
	s_nop 1
	v_add_f32_dpp v42, v42, v42 quad_perm:[2,3,0,1] row_mask:0xf bank_mask:0xf
	s_nop 1
	v_add_f32_dpp v42, v42, v42 row_half_mirror row_mask:0xf bank_mask:0xf
	s_nop 1
	v_add_f32_dpp v42, v42, v42 row_mirror row_mask:0xf bank_mask:0xf
	s_nop 1
	v_add_f32_dpp v42, v42, v42 row_bcast:15 row_mask:0xa bank_mask:0xf
	s_nop 1
	v_add_f32_dpp v42, v42, v42 row_bcast:31 row_mask:0xc bank_mask:0xf
	s_nop 1
	v_readlane_b32 s100, v42, 63
	s_nop 3
	v_mov_b32_e32 v44, s100
	v_fma_f32 v44, v44, v47, v224
	v_rsq_f32_e32 v45, v44
	s_nop 0
	v_mul_f32_e32 v46, v44, v45
	v_mul_f32_e32 v46, v46, v45
	v_fmaak_f32 v46, -0.5, v46, 0x3fc00000
	v_mul_f32_e32 v44, v45, v46
	v_mov_b32_e32 v45, v44
	v_lshlrev_b32_e32 v60, 16, v132
	v_and_b32_e32 v61, 0xffff0000, v132
	v_pk_mul_f32 v[60:61], v[60:61], v[44:45]
	v_pk_fma_f32 v[60:61], v[60:61], v[2:3], v[164:165]
	v_cvt_pk_bf16_f32 v132, v60, v61
	v_lshlrev_b32_e32 v62, 16, v133
	v_and_b32_e32 v63, 0xffff0000, v133
	v_pk_mul_f32 v[62:63], v[62:63], v[44:45]
	v_pk_fma_f32 v[62:63], v[62:63], v[4:5], v[166:167]
	v_cvt_pk_bf16_f32 v133, v62, v63
	v_lshlrev_b32_e32 v64, 16, v134
	v_and_b32_e32 v65, 0xffff0000, v134
	v_pk_mul_f32 v[64:65], v[64:65], v[44:45]
	v_pk_fma_f32 v[64:65], v[64:65], v[6:7], v[168:169]
	v_cvt_pk_bf16_f32 v134, v64, v65
	v_lshlrev_b32_e32 v66, 16, v135
	v_and_b32_e32 v67, 0xffff0000, v135
	v_pk_mul_f32 v[66:67], v[66:67], v[44:45]
	v_pk_fma_f32 v[66:67], v[66:67], v[8:9], v[170:171]
	v_cvt_pk_bf16_f32 v135, v66, v67
	v_lshlrev_b32_e32 v60, 16, v136
	v_and_b32_e32 v61, 0xffff0000, v136
	v_pk_mul_f32 v[60:61], v[60:61], v[44:45]
	v_pk_fma_f32 v[60:61], v[60:61], v[10:11], v[172:173]
	v_cvt_pk_bf16_f32 v136, v60, v61
	v_lshlrev_b32_e32 v62, 16, v137
	v_and_b32_e32 v63, 0xffff0000, v137
	v_pk_mul_f32 v[62:63], v[62:63], v[44:45]
	v_pk_fma_f32 v[62:63], v[62:63], v[12:13], v[174:175]
	v_cvt_pk_bf16_f32 v137, v62, v63
	v_lshlrev_b32_e32 v64, 16, v138
	v_and_b32_e32 v65, 0xffff0000, v138
	v_pk_mul_f32 v[64:65], v[64:65], v[44:45]
	v_pk_fma_f32 v[64:65], v[64:65], v[14:15], v[176:177]
	v_cvt_pk_bf16_f32 v138, v64, v65
	v_lshlrev_b32_e32 v66, 16, v139
	v_and_b32_e32 v67, 0xffff0000, v139
	v_pk_mul_f32 v[66:67], v[66:67], v[44:45]
	v_pk_fma_f32 v[66:67], v[66:67], v[16:17], v[178:179]
	v_cvt_pk_bf16_f32 v139, v66, v67
	v_lshlrev_b32_e32 v60, 16, v140
	v_and_b32_e32 v61, 0xffff0000, v140
	v_pk_mul_f32 v[60:61], v[60:61], v[44:45]
	v_pk_fma_f32 v[60:61], v[60:61], v[18:19], v[180:181]
	v_cvt_pk_bf16_f32 v140, v60, v61
	v_lshlrev_b32_e32 v62, 16, v141
	v_and_b32_e32 v63, 0xffff0000, v141
	v_pk_mul_f32 v[62:63], v[62:63], v[44:45]
	v_pk_fma_f32 v[62:63], v[62:63], v[20:21], v[182:183]
	v_cvt_pk_bf16_f32 v141, v62, v63
	v_lshlrev_b32_e32 v64, 16, v142
	v_and_b32_e32 v65, 0xffff0000, v142
	v_pk_mul_f32 v[64:65], v[64:65], v[44:45]
	v_pk_fma_f32 v[64:65], v[64:65], v[22:23], v[184:185]
	v_cvt_pk_bf16_f32 v142, v64, v65
	v_lshlrev_b32_e32 v66, 16, v143
	v_and_b32_e32 v67, 0xffff0000, v143
	v_pk_mul_f32 v[66:67], v[66:67], v[44:45]
	v_pk_fma_f32 v[66:67], v[66:67], v[24:25], v[186:187]
	v_cvt_pk_bf16_f32 v143, v66, v67
	v_lshlrev_b32_e32 v60, 16, v144
	v_and_b32_e32 v61, 0xffff0000, v144
	v_pk_mul_f32 v[60:61], v[60:61], v[44:45]
	v_pk_fma_f32 v[60:61], v[60:61], v[26:27], v[188:189]
	v_cvt_pk_bf16_f32 v144, v60, v61
	v_lshlrev_b32_e32 v62, 16, v145
	v_and_b32_e32 v63, 0xffff0000, v145
	v_pk_mul_f32 v[62:63], v[62:63], v[44:45]
	v_pk_fma_f32 v[62:63], v[62:63], v[28:29], v[190:191]
	v_cvt_pk_bf16_f32 v145, v62, v63
	v_lshlrev_b32_e32 v64, 16, v146
	v_and_b32_e32 v65, 0xffff0000, v146
	v_pk_mul_f32 v[64:65], v[64:65], v[44:45]
	v_pk_fma_f32 v[64:65], v[64:65], v[30:31], v[192:193]
	v_cvt_pk_bf16_f32 v146, v64, v65
	v_lshlrev_b32_e32 v66, 16, v147
	v_and_b32_e32 v67, 0xffff0000, v147
	v_pk_mul_f32 v[66:67], v[66:67], v[44:45]
	v_pk_fma_f32 v[66:67], v[66:67], v[32:33], v[194:195]
	v_cvt_pk_bf16_f32 v147, v66, v67
	global_store_dwordx4 v39, v[132:135], s[20:21]
	global_store_dwordx4 v39, v[136:139], s[20:21] offset:1024
	global_store_dwordx4 v39, v[140:143], s[20:21] offset:2048
	global_store_dwordx4 v39, v[144:147], s[20:21] offset:3072
	s_add_u32 s20, s20, 0x1000
	s_addc_u32 s21, s21, 0
	global_load_dwordx4 v[132:135], v39, s[10:11]
	global_load_dwordx4 v[136:139], v39, s[10:11] offset:1024
	global_load_dwordx4 v[140:143], v39, s[10:11] offset:2048
	global_load_dwordx4 v[144:147], v39, s[10:11] offset:3072
	s_add_u32 s10, s10, 0x1000
	s_addc_u32 s11, s11, 0
	s_waitcnt vmcnt(24)
	v_lshlrev_b32_e32 v60, 16, v148
	v_and_b32_e32 v61, 0xffff0000, v148
	v_pk_mul_f32 v[42:43], v[60:61], v[60:61]
	v_lshlrev_b32_e32 v62, 16, v149
	v_and_b32_e32 v63, 0xffff0000, v149
	v_pk_fma_f32 v[42:43], v[62:63], v[62:63], v[42:43]
	v_lshlrev_b32_e32 v64, 16, v150
	v_and_b32_e32 v65, 0xffff0000, v150
	v_pk_fma_f32 v[42:43], v[64:65], v[64:65], v[42:43]
	v_lshlrev_b32_e32 v66, 16, v151
	v_and_b32_e32 v67, 0xffff0000, v151
	v_pk_fma_f32 v[42:43], v[66:67], v[66:67], v[42:43]
	v_lshlrev_b32_e32 v60, 16, v152
	v_and_b32_e32 v61, 0xffff0000, v152
	v_pk_fma_f32 v[42:43], v[60:61], v[60:61], v[42:43]
	v_lshlrev_b32_e32 v62, 16, v153
	v_and_b32_e32 v63, 0xffff0000, v153
	v_pk_fma_f32 v[42:43], v[62:63], v[62:63], v[42:43]
	v_lshlrev_b32_e32 v64, 16, v154
	v_and_b32_e32 v65, 0xffff0000, v154
	v_pk_fma_f32 v[42:43], v[64:65], v[64:65], v[42:43]
	v_lshlrev_b32_e32 v66, 16, v155
	v_and_b32_e32 v67, 0xffff0000, v155
	v_pk_fma_f32 v[42:43], v[66:67], v[66:67], v[42:43]
	v_lshlrev_b32_e32 v60, 16, v156
	v_and_b32_e32 v61, 0xffff0000, v156
	v_pk_fma_f32 v[42:43], v[60:61], v[60:61], v[42:43]
	v_lshlrev_b32_e32 v62, 16, v157
	v_and_b32_e32 v63, 0xffff0000, v157
	v_pk_fma_f32 v[42:43], v[62:63], v[62:63], v[42:43]
	v_lshlrev_b32_e32 v64, 16, v158
	v_and_b32_e32 v65, 0xffff0000, v158
	v_pk_fma_f32 v[42:43], v[64:65], v[64:65], v[42:43]
	v_lshlrev_b32_e32 v66, 16, v159
	v_and_b32_e32 v67, 0xffff0000, v159
	v_pk_fma_f32 v[42:43], v[66:67], v[66:67], v[42:43]
	v_lshlrev_b32_e32 v60, 16, v160
	v_and_b32_e32 v61, 0xffff0000, v160
	v_pk_fma_f32 v[42:43], v[60:61], v[60:61], v[42:43]
	v_lshlrev_b32_e32 v62, 16, v161
	v_and_b32_e32 v63, 0xffff0000, v161
	v_pk_fma_f32 v[42:43], v[62:63], v[62:63], v[42:43]
	v_lshlrev_b32_e32 v64, 16, v162
	v_and_b32_e32 v65, 0xffff0000, v162
	v_pk_fma_f32 v[42:43], v[64:65], v[64:65], v[42:43]
	v_lshlrev_b32_e32 v66, 16, v163
	v_and_b32_e32 v67, 0xffff0000, v163
	v_pk_fma_f32 v[42:43], v[66:67], v[66:67], v[42:43]
	v_add_f32_e32 v42, v42, v43
	s_nop 1
	v_add_f32_dpp v42, v42, v42 quad_perm:[1,0,3,2] row_mask:0xf bank_mask:0xf
	s_nop 1
	v_add_f32_dpp v42, v42, v42 quad_perm:[2,3,0,1] row_mask:0xf bank_mask:0xf
	s_nop 1
	v_add_f32_dpp v42, v42, v42 row_half_mirror row_mask:0xf bank_mask:0xf
	s_nop 1
	v_add_f32_dpp v42, v42, v42 row_mirror row_mask:0xf bank_mask:0xf
	s_nop 1
	v_add_f32_dpp v42, v42, v42 row_bcast:15 row_mask:0xa bank_mask:0xf
	s_nop 1
	v_add_f32_dpp v42, v42, v42 row_bcast:31 row_mask:0xc bank_mask:0xf
	s_nop 1
	v_readlane_b32 s100, v42, 63
	s_nop 3
	v_mov_b32_e32 v44, s100
	v_fma_f32 v44, v44, v47, v224
	v_rsq_f32_e32 v45, v44
	s_nop 0
	v_mul_f32_e32 v46, v44, v45
	v_mul_f32_e32 v46, v46, v45
	v_fmaak_f32 v46, -0.5, v46, 0x3fc00000
	v_mul_f32_e32 v44, v45, v46
	v_mov_b32_e32 v45, v44
	v_lshlrev_b32_e32 v60, 16, v148
	v_and_b32_e32 v61, 0xffff0000, v148
	v_pk_mul_f32 v[60:61], v[60:61], v[44:45]
	v_pk_fma_f32 v[60:61], v[60:61], v[2:3], v[164:165]
	v_cvt_pk_bf16_f32 v148, v60, v61
	v_lshlrev_b32_e32 v62, 16, v149
	v_and_b32_e32 v63, 0xffff0000, v149
	v_pk_mul_f32 v[62:63], v[62:63], v[44:45]
	v_pk_fma_f32 v[62:63], v[62:63], v[4:5], v[166:167]
	v_cvt_pk_bf16_f32 v149, v62, v63
	v_lshlrev_b32_e32 v64, 16, v150
	v_and_b32_e32 v65, 0xffff0000, v150
	v_pk_mul_f32 v[64:65], v[64:65], v[44:45]
	v_pk_fma_f32 v[64:65], v[64:65], v[6:7], v[168:169]
	v_cvt_pk_bf16_f32 v150, v64, v65
	v_lshlrev_b32_e32 v66, 16, v151
	v_and_b32_e32 v67, 0xffff0000, v151
	v_pk_mul_f32 v[66:67], v[66:67], v[44:45]
	v_pk_fma_f32 v[66:67], v[66:67], v[8:9], v[170:171]
	v_cvt_pk_bf16_f32 v151, v66, v67
	v_lshlrev_b32_e32 v60, 16, v152
	v_and_b32_e32 v61, 0xffff0000, v152
	v_pk_mul_f32 v[60:61], v[60:61], v[44:45]
	v_pk_fma_f32 v[60:61], v[60:61], v[10:11], v[172:173]
	v_cvt_pk_bf16_f32 v152, v60, v61
	v_lshlrev_b32_e32 v62, 16, v153
	v_and_b32_e32 v63, 0xffff0000, v153
	v_pk_mul_f32 v[62:63], v[62:63], v[44:45]
	v_pk_fma_f32 v[62:63], v[62:63], v[12:13], v[174:175]
	v_cvt_pk_bf16_f32 v153, v62, v63
	v_lshlrev_b32_e32 v64, 16, v154
	v_and_b32_e32 v65, 0xffff0000, v154
	v_pk_mul_f32 v[64:65], v[64:65], v[44:45]
	v_pk_fma_f32 v[64:65], v[64:65], v[14:15], v[176:177]
	v_cvt_pk_bf16_f32 v154, v64, v65
	v_lshlrev_b32_e32 v66, 16, v155
	v_and_b32_e32 v67, 0xffff0000, v155
	v_pk_mul_f32 v[66:67], v[66:67], v[44:45]
	v_pk_fma_f32 v[66:67], v[66:67], v[16:17], v[178:179]
	v_cvt_pk_bf16_f32 v155, v66, v67
	v_lshlrev_b32_e32 v60, 16, v156
	v_and_b32_e32 v61, 0xffff0000, v156
	v_pk_mul_f32 v[60:61], v[60:61], v[44:45]
	v_pk_fma_f32 v[60:61], v[60:61], v[18:19], v[180:181]
	v_cvt_pk_bf16_f32 v156, v60, v61
	v_lshlrev_b32_e32 v62, 16, v157
	v_and_b32_e32 v63, 0xffff0000, v157
	v_pk_mul_f32 v[62:63], v[62:63], v[44:45]
	v_pk_fma_f32 v[62:63], v[62:63], v[20:21], v[182:183]
	v_cvt_pk_bf16_f32 v157, v62, v63
	v_lshlrev_b32_e32 v64, 16, v158
	v_and_b32_e32 v65, 0xffff0000, v158
	v_pk_mul_f32 v[64:65], v[64:65], v[44:45]
	v_pk_fma_f32 v[64:65], v[64:65], v[22:23], v[184:185]
	v_cvt_pk_bf16_f32 v158, v64, v65
	v_lshlrev_b32_e32 v66, 16, v159
	v_and_b32_e32 v67, 0xffff0000, v159
	v_pk_mul_f32 v[66:67], v[66:67], v[44:45]
	v_pk_fma_f32 v[66:67], v[66:67], v[24:25], v[186:187]
	v_cvt_pk_bf16_f32 v159, v66, v67
	v_lshlrev_b32_e32 v60, 16, v160
	v_and_b32_e32 v61, 0xffff0000, v160
	v_pk_mul_f32 v[60:61], v[60:61], v[44:45]
	v_pk_fma_f32 v[60:61], v[60:61], v[26:27], v[188:189]
	v_cvt_pk_bf16_f32 v160, v60, v61
	v_lshlrev_b32_e32 v62, 16, v161
	v_and_b32_e32 v63, 0xffff0000, v161
	v_pk_mul_f32 v[62:63], v[62:63], v[44:45]
	v_pk_fma_f32 v[62:63], v[62:63], v[28:29], v[190:191]
	v_cvt_pk_bf16_f32 v161, v62, v63
	v_lshlrev_b32_e32 v64, 16, v162
	v_and_b32_e32 v65, 0xffff0000, v162
	v_pk_mul_f32 v[64:65], v[64:65], v[44:45]
	v_pk_fma_f32 v[64:65], v[64:65], v[30:31], v[192:193]
	v_cvt_pk_bf16_f32 v162, v64, v65
	v_lshlrev_b32_e32 v66, 16, v163
	v_and_b32_e32 v67, 0xffff0000, v163
	v_pk_mul_f32 v[66:67], v[66:67], v[44:45]
	v_pk_fma_f32 v[66:67], v[66:67], v[32:33], v[194:195]
	v_cvt_pk_bf16_f32 v163, v66, v67
	global_store_dwordx4 v39, v[148:151], s[20:21]
	global_store_dwordx4 v39, v[152:155], s[20:21] offset:1024
	global_store_dwordx4 v39, v[156:159], s[20:21] offset:2048
	global_store_dwordx4 v39, v[160:163], s[20:21] offset:3072
	s_add_u32 s20, s20, 0x1000
	s_addc_u32 s21, s21, 0
	global_load_dwordx4 v[148:151], v39, s[10:11]
	global_load_dwordx4 v[152:155], v39, s[10:11] offset:1024
	global_load_dwordx4 v[156:159], v39, s[10:11] offset:2048
	global_load_dwordx4 v[160:163], v39, s[10:11] offset:3072
	s_add_u32 s10, s10, 0x1000
	s_addc_u32 s11, s11, 0
	s_waitcnt vmcnt(24)
	v_lshlrev_b32_e32 v60, 16, v100
	v_and_b32_e32 v61, 0xffff0000, v100
	v_pk_mul_f32 v[42:43], v[60:61], v[60:61]
	v_lshlrev_b32_e32 v62, 16, v101
	v_and_b32_e32 v63, 0xffff0000, v101
	v_pk_fma_f32 v[42:43], v[62:63], v[62:63], v[42:43]
	v_lshlrev_b32_e32 v64, 16, v102
	v_and_b32_e32 v65, 0xffff0000, v102
	v_pk_fma_f32 v[42:43], v[64:65], v[64:65], v[42:43]
	v_lshlrev_b32_e32 v66, 16, v103
	v_and_b32_e32 v67, 0xffff0000, v103
	v_pk_fma_f32 v[42:43], v[66:67], v[66:67], v[42:43]
	v_lshlrev_b32_e32 v60, 16, v104
	v_and_b32_e32 v61, 0xffff0000, v104
	v_pk_fma_f32 v[42:43], v[60:61], v[60:61], v[42:43]
	v_lshlrev_b32_e32 v62, 16, v105
	v_and_b32_e32 v63, 0xffff0000, v105
	v_pk_fma_f32 v[42:43], v[62:63], v[62:63], v[42:43]
	v_lshlrev_b32_e32 v64, 16, v106
	v_and_b32_e32 v65, 0xffff0000, v106
	v_pk_fma_f32 v[42:43], v[64:65], v[64:65], v[42:43]
	v_lshlrev_b32_e32 v66, 16, v107
	v_and_b32_e32 v67, 0xffff0000, v107
	v_pk_fma_f32 v[42:43], v[66:67], v[66:67], v[42:43]
	v_lshlrev_b32_e32 v60, 16, v108
	v_and_b32_e32 v61, 0xffff0000, v108
	v_pk_fma_f32 v[42:43], v[60:61], v[60:61], v[42:43]
	v_lshlrev_b32_e32 v62, 16, v109
	v_and_b32_e32 v63, 0xffff0000, v109
	v_pk_fma_f32 v[42:43], v[62:63], v[62:63], v[42:43]
	v_lshlrev_b32_e32 v64, 16, v110
	v_and_b32_e32 v65, 0xffff0000, v110
	v_pk_fma_f32 v[42:43], v[64:65], v[64:65], v[42:43]
	v_lshlrev_b32_e32 v66, 16, v111
	v_and_b32_e32 v67, 0xffff0000, v111
	v_pk_fma_f32 v[42:43], v[66:67], v[66:67], v[42:43]
	v_lshlrev_b32_e32 v60, 16, v112
	v_and_b32_e32 v61, 0xffff0000, v112
	v_pk_fma_f32 v[42:43], v[60:61], v[60:61], v[42:43]
	v_lshlrev_b32_e32 v62, 16, v113
	v_and_b32_e32 v63, 0xffff0000, v113
	v_pk_fma_f32 v[42:43], v[62:63], v[62:63], v[42:43]
	v_lshlrev_b32_e32 v64, 16, v114
	v_and_b32_e32 v65, 0xffff0000, v114
	v_pk_fma_f32 v[42:43], v[64:65], v[64:65], v[42:43]
	v_lshlrev_b32_e32 v66, 16, v115
	v_and_b32_e32 v67, 0xffff0000, v115
	v_pk_fma_f32 v[42:43], v[66:67], v[66:67], v[42:43]
	v_add_f32_e32 v42, v42, v43
	s_nop 1
	v_add_f32_dpp v42, v42, v42 quad_perm:[1,0,3,2] row_mask:0xf bank_mask:0xf
	s_nop 1
	v_add_f32_dpp v42, v42, v42 quad_perm:[2,3,0,1] row_mask:0xf bank_mask:0xf
	s_nop 1
	v_add_f32_dpp v42, v42, v42 row_half_mirror row_mask:0xf bank_mask:0xf
	s_nop 1
	v_add_f32_dpp v42, v42, v42 row_mirror row_mask:0xf bank_mask:0xf
	s_nop 1
	v_add_f32_dpp v42, v42, v42 row_bcast:15 row_mask:0xa bank_mask:0xf
	s_nop 1
	v_add_f32_dpp v42, v42, v42 row_bcast:31 row_mask:0xc bank_mask:0xf
	s_nop 1
	v_readlane_b32 s100, v42, 63
	s_nop 3
	v_mov_b32_e32 v44, s100
	v_fma_f32 v44, v44, v47, v224
	v_rsq_f32_e32 v45, v44
	s_nop 0
	v_mul_f32_e32 v46, v44, v45
	v_mul_f32_e32 v46, v46, v45
	v_fmaak_f32 v46, -0.5, v46, 0x3fc00000
	v_mul_f32_e32 v44, v45, v46
	v_mov_b32_e32 v45, v44
	v_lshlrev_b32_e32 v60, 16, v100
	v_and_b32_e32 v61, 0xffff0000, v100
	v_pk_mul_f32 v[60:61], v[60:61], v[44:45]
	v_pk_fma_f32 v[60:61], v[60:61], v[2:3], v[164:165]
	v_cvt_pk_bf16_f32 v100, v60, v61
	v_lshlrev_b32_e32 v62, 16, v101
	v_and_b32_e32 v63, 0xffff0000, v101
	v_pk_mul_f32 v[62:63], v[62:63], v[44:45]
	v_pk_fma_f32 v[62:63], v[62:63], v[4:5], v[166:167]
	v_cvt_pk_bf16_f32 v101, v62, v63
	v_lshlrev_b32_e32 v64, 16, v102
	v_and_b32_e32 v65, 0xffff0000, v102
	v_pk_mul_f32 v[64:65], v[64:65], v[44:45]
	v_pk_fma_f32 v[64:65], v[64:65], v[6:7], v[168:169]
	v_cvt_pk_bf16_f32 v102, v64, v65
	v_lshlrev_b32_e32 v66, 16, v103
	v_and_b32_e32 v67, 0xffff0000, v103
	v_pk_mul_f32 v[66:67], v[66:67], v[44:45]
	v_pk_fma_f32 v[66:67], v[66:67], v[8:9], v[170:171]
	v_cvt_pk_bf16_f32 v103, v66, v67
	v_lshlrev_b32_e32 v60, 16, v104
	v_and_b32_e32 v61, 0xffff0000, v104
	v_pk_mul_f32 v[60:61], v[60:61], v[44:45]
	v_pk_fma_f32 v[60:61], v[60:61], v[10:11], v[172:173]
	v_cvt_pk_bf16_f32 v104, v60, v61
	v_lshlrev_b32_e32 v62, 16, v105
	v_and_b32_e32 v63, 0xffff0000, v105
	v_pk_mul_f32 v[62:63], v[62:63], v[44:45]
	v_pk_fma_f32 v[62:63], v[62:63], v[12:13], v[174:175]
	v_cvt_pk_bf16_f32 v105, v62, v63
	v_lshlrev_b32_e32 v64, 16, v106
	v_and_b32_e32 v65, 0xffff0000, v106
	v_pk_mul_f32 v[64:65], v[64:65], v[44:45]
	v_pk_fma_f32 v[64:65], v[64:65], v[14:15], v[176:177]
	v_cvt_pk_bf16_f32 v106, v64, v65
	v_lshlrev_b32_e32 v66, 16, v107
	v_and_b32_e32 v67, 0xffff0000, v107
	v_pk_mul_f32 v[66:67], v[66:67], v[44:45]
	v_pk_fma_f32 v[66:67], v[66:67], v[16:17], v[178:179]
	v_cvt_pk_bf16_f32 v107, v66, v67
	v_lshlrev_b32_e32 v60, 16, v108
	v_and_b32_e32 v61, 0xffff0000, v108
	v_pk_mul_f32 v[60:61], v[60:61], v[44:45]
	v_pk_fma_f32 v[60:61], v[60:61], v[18:19], v[180:181]
	v_cvt_pk_bf16_f32 v108, v60, v61
	v_lshlrev_b32_e32 v62, 16, v109
	v_and_b32_e32 v63, 0xffff0000, v109
	v_pk_mul_f32 v[62:63], v[62:63], v[44:45]
	v_pk_fma_f32 v[62:63], v[62:63], v[20:21], v[182:183]
	v_cvt_pk_bf16_f32 v109, v62, v63
	v_lshlrev_b32_e32 v64, 16, v110
	v_and_b32_e32 v65, 0xffff0000, v110
	v_pk_mul_f32 v[64:65], v[64:65], v[44:45]
	v_pk_fma_f32 v[64:65], v[64:65], v[22:23], v[184:185]
	v_cvt_pk_bf16_f32 v110, v64, v65
	v_lshlrev_b32_e32 v66, 16, v111
	v_and_b32_e32 v67, 0xffff0000, v111
	v_pk_mul_f32 v[66:67], v[66:67], v[44:45]
	v_pk_fma_f32 v[66:67], v[66:67], v[24:25], v[186:187]
	v_cvt_pk_bf16_f32 v111, v66, v67
	v_lshlrev_b32_e32 v60, 16, v112
	v_and_b32_e32 v61, 0xffff0000, v112
	v_pk_mul_f32 v[60:61], v[60:61], v[44:45]
	v_pk_fma_f32 v[60:61], v[60:61], v[26:27], v[188:189]
	v_cvt_pk_bf16_f32 v112, v60, v61
	v_lshlrev_b32_e32 v62, 16, v113
	v_and_b32_e32 v63, 0xffff0000, v113
	v_pk_mul_f32 v[62:63], v[62:63], v[44:45]
	v_pk_fma_f32 v[62:63], v[62:63], v[28:29], v[190:191]
	v_cvt_pk_bf16_f32 v113, v62, v63
	v_lshlrev_b32_e32 v64, 16, v114
	v_and_b32_e32 v65, 0xffff0000, v114
	v_pk_mul_f32 v[64:65], v[64:65], v[44:45]
	v_pk_fma_f32 v[64:65], v[64:65], v[30:31], v[192:193]
	v_cvt_pk_bf16_f32 v114, v64, v65
	v_lshlrev_b32_e32 v66, 16, v115
	v_and_b32_e32 v67, 0xffff0000, v115
	v_pk_mul_f32 v[66:67], v[66:67], v[44:45]
	v_pk_fma_f32 v[66:67], v[66:67], v[32:33], v[194:195]
	v_cvt_pk_bf16_f32 v115, v66, v67
	global_store_dwordx4 v39, v[100:103], s[20:21]
	global_store_dwordx4 v39, v[104:107], s[20:21] offset:1024
	global_store_dwordx4 v39, v[108:111], s[20:21] offset:2048
	global_store_dwordx4 v39, v[112:115], s[20:21] offset:3072
	s_add_u32 s20, s20, 0x1000
	s_addc_u32 s21, s21, 0
	s_waitcnt vmcnt(20)
	v_lshlrev_b32_e32 v60, 16, v116
	v_and_b32_e32 v61, 0xffff0000, v116
	v_pk_mul_f32 v[42:43], v[60:61], v[60:61]
	v_lshlrev_b32_e32 v62, 16, v117
	v_and_b32_e32 v63, 0xffff0000, v117
	v_pk_fma_f32 v[42:43], v[62:63], v[62:63], v[42:43]
	v_lshlrev_b32_e32 v64, 16, v118
	v_and_b32_e32 v65, 0xffff0000, v118
	v_pk_fma_f32 v[42:43], v[64:65], v[64:65], v[42:43]
	v_lshlrev_b32_e32 v66, 16, v119
	v_and_b32_e32 v67, 0xffff0000, v119
	v_pk_fma_f32 v[42:43], v[66:67], v[66:67], v[42:43]
	v_lshlrev_b32_e32 v60, 16, v120
	v_and_b32_e32 v61, 0xffff0000, v120
	v_pk_fma_f32 v[42:43], v[60:61], v[60:61], v[42:43]
	v_lshlrev_b32_e32 v62, 16, v121
	v_and_b32_e32 v63, 0xffff0000, v121
	v_pk_fma_f32 v[42:43], v[62:63], v[62:63], v[42:43]
	v_lshlrev_b32_e32 v64, 16, v122
	v_and_b32_e32 v65, 0xffff0000, v122
	v_pk_fma_f32 v[42:43], v[64:65], v[64:65], v[42:43]
	v_lshlrev_b32_e32 v66, 16, v123
	v_and_b32_e32 v67, 0xffff0000, v123
	v_pk_fma_f32 v[42:43], v[66:67], v[66:67], v[42:43]
	v_lshlrev_b32_e32 v60, 16, v124
	v_and_b32_e32 v61, 0xffff0000, v124
	v_pk_fma_f32 v[42:43], v[60:61], v[60:61], v[42:43]
	v_lshlrev_b32_e32 v62, 16, v125
	v_and_b32_e32 v63, 0xffff0000, v125
	v_pk_fma_f32 v[42:43], v[62:63], v[62:63], v[42:43]
	v_lshlrev_b32_e32 v64, 16, v126
	v_and_b32_e32 v65, 0xffff0000, v126
	v_pk_fma_f32 v[42:43], v[64:65], v[64:65], v[42:43]
	v_lshlrev_b32_e32 v66, 16, v127
	v_and_b32_e32 v67, 0xffff0000, v127
	v_pk_fma_f32 v[42:43], v[66:67], v[66:67], v[42:43]
	v_lshlrev_b32_e32 v60, 16, v128
	v_and_b32_e32 v61, 0xffff0000, v128
	v_pk_fma_f32 v[42:43], v[60:61], v[60:61], v[42:43]
	v_lshlrev_b32_e32 v62, 16, v129
	v_and_b32_e32 v63, 0xffff0000, v129
	v_pk_fma_f32 v[42:43], v[62:63], v[62:63], v[42:43]
	v_lshlrev_b32_e32 v64, 16, v130
	v_and_b32_e32 v65, 0xffff0000, v130
	v_pk_fma_f32 v[42:43], v[64:65], v[64:65], v[42:43]
	v_lshlrev_b32_e32 v66, 16, v131
	v_and_b32_e32 v67, 0xffff0000, v131
	v_pk_fma_f32 v[42:43], v[66:67], v[66:67], v[42:43]
	v_add_f32_e32 v42, v42, v43
	s_nop 1
	v_add_f32_dpp v42, v42, v42 quad_perm:[1,0,3,2] row_mask:0xf bank_mask:0xf
	s_nop 1
	v_add_f32_dpp v42, v42, v42 quad_perm:[2,3,0,1] row_mask:0xf bank_mask:0xf
	s_nop 1
	v_add_f32_dpp v42, v42, v42 row_half_mirror row_mask:0xf bank_mask:0xf
	s_nop 1
	v_add_f32_dpp v42, v42, v42 row_mirror row_mask:0xf bank_mask:0xf
	s_nop 1
	v_add_f32_dpp v42, v42, v42 row_bcast:15 row_mask:0xa bank_mask:0xf
	s_nop 1
	v_add_f32_dpp v42, v42, v42 row_bcast:31 row_mask:0xc bank_mask:0xf
	s_nop 1
	v_readlane_b32 s100, v42, 63
	s_nop 3
	v_mov_b32_e32 v44, s100
	v_fma_f32 v44, v44, v47, v224
	v_rsq_f32_e32 v45, v44
	s_nop 0
	v_mul_f32_e32 v46, v44, v45
	v_mul_f32_e32 v46, v46, v45
	v_fmaak_f32 v46, -0.5, v46, 0x3fc00000
	v_mul_f32_e32 v44, v45, v46
	v_mov_b32_e32 v45, v44
	v_lshlrev_b32_e32 v60, 16, v116
	v_and_b32_e32 v61, 0xffff0000, v116
	v_pk_mul_f32 v[60:61], v[60:61], v[44:45]
	v_pk_fma_f32 v[60:61], v[60:61], v[2:3], v[164:165]
	v_cvt_pk_bf16_f32 v116, v60, v61
	v_lshlrev_b32_e32 v62, 16, v117
	v_and_b32_e32 v63, 0xffff0000, v117
	v_pk_mul_f32 v[62:63], v[62:63], v[44:45]
	v_pk_fma_f32 v[62:63], v[62:63], v[4:5], v[166:167]
	v_cvt_pk_bf16_f32 v117, v62, v63
	v_lshlrev_b32_e32 v64, 16, v118
	v_and_b32_e32 v65, 0xffff0000, v118
	v_pk_mul_f32 v[64:65], v[64:65], v[44:45]
	v_pk_fma_f32 v[64:65], v[64:65], v[6:7], v[168:169]
	v_cvt_pk_bf16_f32 v118, v64, v65
	v_lshlrev_b32_e32 v66, 16, v119
	v_and_b32_e32 v67, 0xffff0000, v119
	v_pk_mul_f32 v[66:67], v[66:67], v[44:45]
	v_pk_fma_f32 v[66:67], v[66:67], v[8:9], v[170:171]
	v_cvt_pk_bf16_f32 v119, v66, v67
	v_lshlrev_b32_e32 v60, 16, v120
	v_and_b32_e32 v61, 0xffff0000, v120
	v_pk_mul_f32 v[60:61], v[60:61], v[44:45]
	v_pk_fma_f32 v[60:61], v[60:61], v[10:11], v[172:173]
	v_cvt_pk_bf16_f32 v120, v60, v61
	v_lshlrev_b32_e32 v62, 16, v121
	v_and_b32_e32 v63, 0xffff0000, v121
	v_pk_mul_f32 v[62:63], v[62:63], v[44:45]
	v_pk_fma_f32 v[62:63], v[62:63], v[12:13], v[174:175]
	v_cvt_pk_bf16_f32 v121, v62, v63
	v_lshlrev_b32_e32 v64, 16, v122
	v_and_b32_e32 v65, 0xffff0000, v122
	v_pk_mul_f32 v[64:65], v[64:65], v[44:45]
	v_pk_fma_f32 v[64:65], v[64:65], v[14:15], v[176:177]
	v_cvt_pk_bf16_f32 v122, v64, v65
	v_lshlrev_b32_e32 v66, 16, v123
	v_and_b32_e32 v67, 0xffff0000, v123
	v_pk_mul_f32 v[66:67], v[66:67], v[44:45]
	v_pk_fma_f32 v[66:67], v[66:67], v[16:17], v[178:179]
	v_cvt_pk_bf16_f32 v123, v66, v67
	v_lshlrev_b32_e32 v60, 16, v124
	v_and_b32_e32 v61, 0xffff0000, v124
	v_pk_mul_f32 v[60:61], v[60:61], v[44:45]
	v_pk_fma_f32 v[60:61], v[60:61], v[18:19], v[180:181]
	v_cvt_pk_bf16_f32 v124, v60, v61
	v_lshlrev_b32_e32 v62, 16, v125
	v_and_b32_e32 v63, 0xffff0000, v125
	v_pk_mul_f32 v[62:63], v[62:63], v[44:45]
	v_pk_fma_f32 v[62:63], v[62:63], v[20:21], v[182:183]
	v_cvt_pk_bf16_f32 v125, v62, v63
	v_lshlrev_b32_e32 v64, 16, v126
	v_and_b32_e32 v65, 0xffff0000, v126
	v_pk_mul_f32 v[64:65], v[64:65], v[44:45]
	v_pk_fma_f32 v[64:65], v[64:65], v[22:23], v[184:185]
	v_cvt_pk_bf16_f32 v126, v64, v65
	v_lshlrev_b32_e32 v66, 16, v127
	v_and_b32_e32 v67, 0xffff0000, v127
	v_pk_mul_f32 v[66:67], v[66:67], v[44:45]
	v_pk_fma_f32 v[66:67], v[66:67], v[24:25], v[186:187]
	v_cvt_pk_bf16_f32 v127, v66, v67
	v_lshlrev_b32_e32 v60, 16, v128
	v_and_b32_e32 v61, 0xffff0000, v128
	v_pk_mul_f32 v[60:61], v[60:61], v[44:45]
	v_pk_fma_f32 v[60:61], v[60:61], v[26:27], v[188:189]
	v_cvt_pk_bf16_f32 v128, v60, v61
	v_lshlrev_b32_e32 v62, 16, v129
	v_and_b32_e32 v63, 0xffff0000, v129
	v_pk_mul_f32 v[62:63], v[62:63], v[44:45]
	v_pk_fma_f32 v[62:63], v[62:63], v[28:29], v[190:191]
	v_cvt_pk_bf16_f32 v129, v62, v63
	v_lshlrev_b32_e32 v64, 16, v130
	v_and_b32_e32 v65, 0xffff0000, v130
	v_pk_mul_f32 v[64:65], v[64:65], v[44:45]
	v_pk_fma_f32 v[64:65], v[64:65], v[30:31], v[192:193]
	v_cvt_pk_bf16_f32 v130, v64, v65
	v_lshlrev_b32_e32 v66, 16, v131
	v_and_b32_e32 v67, 0xffff0000, v131
	v_pk_mul_f32 v[66:67], v[66:67], v[44:45]
	v_pk_fma_f32 v[66:67], v[66:67], v[32:33], v[194:195]
	v_cvt_pk_bf16_f32 v131, v66, v67
	global_store_dwordx4 v39, v[116:119], s[20:21]
	global_store_dwordx4 v39, v[120:123], s[20:21] offset:1024
	global_store_dwordx4 v39, v[124:127], s[20:21] offset:2048
	global_store_dwordx4 v39, v[128:131], s[20:21] offset:3072
	s_add_u32 s20, s20, 0x1000
	s_addc_u32 s21, s21, 0
	s_waitcnt vmcnt(16)
	v_lshlrev_b32_e32 v60, 16, v132
	v_and_b32_e32 v61, 0xffff0000, v132
	v_pk_mul_f32 v[42:43], v[60:61], v[60:61]
	v_lshlrev_b32_e32 v62, 16, v133
	v_and_b32_e32 v63, 0xffff0000, v133
	v_pk_fma_f32 v[42:43], v[62:63], v[62:63], v[42:43]
	v_lshlrev_b32_e32 v64, 16, v134
	v_and_b32_e32 v65, 0xffff0000, v134
	v_pk_fma_f32 v[42:43], v[64:65], v[64:65], v[42:43]
	v_lshlrev_b32_e32 v66, 16, v135
	v_and_b32_e32 v67, 0xffff0000, v135
	v_pk_fma_f32 v[42:43], v[66:67], v[66:67], v[42:43]
	v_lshlrev_b32_e32 v60, 16, v136
	v_and_b32_e32 v61, 0xffff0000, v136
	v_pk_fma_f32 v[42:43], v[60:61], v[60:61], v[42:43]
	v_lshlrev_b32_e32 v62, 16, v137
	v_and_b32_e32 v63, 0xffff0000, v137
	v_pk_fma_f32 v[42:43], v[62:63], v[62:63], v[42:43]
	v_lshlrev_b32_e32 v64, 16, v138
	v_and_b32_e32 v65, 0xffff0000, v138
	v_pk_fma_f32 v[42:43], v[64:65], v[64:65], v[42:43]
	v_lshlrev_b32_e32 v66, 16, v139
	v_and_b32_e32 v67, 0xffff0000, v139
	v_pk_fma_f32 v[42:43], v[66:67], v[66:67], v[42:43]
	v_lshlrev_b32_e32 v60, 16, v140
	v_and_b32_e32 v61, 0xffff0000, v140
	v_pk_fma_f32 v[42:43], v[60:61], v[60:61], v[42:43]
	v_lshlrev_b32_e32 v62, 16, v141
	v_and_b32_e32 v63, 0xffff0000, v141
	v_pk_fma_f32 v[42:43], v[62:63], v[62:63], v[42:43]
	v_lshlrev_b32_e32 v64, 16, v142
	v_and_b32_e32 v65, 0xffff0000, v142
	v_pk_fma_f32 v[42:43], v[64:65], v[64:65], v[42:43]
	v_lshlrev_b32_e32 v66, 16, v143
	v_and_b32_e32 v67, 0xffff0000, v143
	v_pk_fma_f32 v[42:43], v[66:67], v[66:67], v[42:43]
	v_lshlrev_b32_e32 v60, 16, v144
	v_and_b32_e32 v61, 0xffff0000, v144
	v_pk_fma_f32 v[42:43], v[60:61], v[60:61], v[42:43]
	v_lshlrev_b32_e32 v62, 16, v145
	v_and_b32_e32 v63, 0xffff0000, v145
	v_pk_fma_f32 v[42:43], v[62:63], v[62:63], v[42:43]
	v_lshlrev_b32_e32 v64, 16, v146
	v_and_b32_e32 v65, 0xffff0000, v146
	v_pk_fma_f32 v[42:43], v[64:65], v[64:65], v[42:43]
	v_lshlrev_b32_e32 v66, 16, v147
	v_and_b32_e32 v67, 0xffff0000, v147
	v_pk_fma_f32 v[42:43], v[66:67], v[66:67], v[42:43]
	v_add_f32_e32 v42, v42, v43
	s_nop 1
	v_add_f32_dpp v42, v42, v42 quad_perm:[1,0,3,2] row_mask:0xf bank_mask:0xf
	s_nop 1
	v_add_f32_dpp v42, v42, v42 quad_perm:[2,3,0,1] row_mask:0xf bank_mask:0xf
	s_nop 1
	v_add_f32_dpp v42, v42, v42 row_half_mirror row_mask:0xf bank_mask:0xf
	s_nop 1
	v_add_f32_dpp v42, v42, v42 row_mirror row_mask:0xf bank_mask:0xf
	s_nop 1
	v_add_f32_dpp v42, v42, v42 row_bcast:15 row_mask:0xa bank_mask:0xf
	s_nop 1
	v_add_f32_dpp v42, v42, v42 row_bcast:31 row_mask:0xc bank_mask:0xf
	s_nop 1
	v_readlane_b32 s100, v42, 63
	s_nop 3
	v_mov_b32_e32 v44, s100
	v_fma_f32 v44, v44, v47, v224
	v_rsq_f32_e32 v45, v44
	s_nop 0
	v_mul_f32_e32 v46, v44, v45
	v_mul_f32_e32 v46, v46, v45
	v_fmaak_f32 v46, -0.5, v46, 0x3fc00000
	v_mul_f32_e32 v44, v45, v46
	v_mov_b32_e32 v45, v44
	v_lshlrev_b32_e32 v60, 16, v132
	v_and_b32_e32 v61, 0xffff0000, v132
	v_pk_mul_f32 v[60:61], v[60:61], v[44:45]
	v_pk_fma_f32 v[60:61], v[60:61], v[2:3], v[164:165]
	v_cvt_pk_bf16_f32 v132, v60, v61
	v_lshlrev_b32_e32 v62, 16, v133
	v_and_b32_e32 v63, 0xffff0000, v133
	v_pk_mul_f32 v[62:63], v[62:63], v[44:45]
	v_pk_fma_f32 v[62:63], v[62:63], v[4:5], v[166:167]
	v_cvt_pk_bf16_f32 v133, v62, v63
	v_lshlrev_b32_e32 v64, 16, v134
	v_and_b32_e32 v65, 0xffff0000, v134
	v_pk_mul_f32 v[64:65], v[64:65], v[44:45]
	v_pk_fma_f32 v[64:65], v[64:65], v[6:7], v[168:169]
	v_cvt_pk_bf16_f32 v134, v64, v65
	v_lshlrev_b32_e32 v66, 16, v135
	v_and_b32_e32 v67, 0xffff0000, v135
	v_pk_mul_f32 v[66:67], v[66:67], v[44:45]
	v_pk_fma_f32 v[66:67], v[66:67], v[8:9], v[170:171]
	v_cvt_pk_bf16_f32 v135, v66, v67
	v_lshlrev_b32_e32 v60, 16, v136
	v_and_b32_e32 v61, 0xffff0000, v136
	v_pk_mul_f32 v[60:61], v[60:61], v[44:45]
	v_pk_fma_f32 v[60:61], v[60:61], v[10:11], v[172:173]
	v_cvt_pk_bf16_f32 v136, v60, v61
	v_lshlrev_b32_e32 v62, 16, v137
	v_and_b32_e32 v63, 0xffff0000, v137
	v_pk_mul_f32 v[62:63], v[62:63], v[44:45]
	v_pk_fma_f32 v[62:63], v[62:63], v[12:13], v[174:175]
	v_cvt_pk_bf16_f32 v137, v62, v63
	v_lshlrev_b32_e32 v64, 16, v138
	v_and_b32_e32 v65, 0xffff0000, v138
	v_pk_mul_f32 v[64:65], v[64:65], v[44:45]
	v_pk_fma_f32 v[64:65], v[64:65], v[14:15], v[176:177]
	v_cvt_pk_bf16_f32 v138, v64, v65
	v_lshlrev_b32_e32 v66, 16, v139
	v_and_b32_e32 v67, 0xffff0000, v139
	v_pk_mul_f32 v[66:67], v[66:67], v[44:45]
	v_pk_fma_f32 v[66:67], v[66:67], v[16:17], v[178:179]
	v_cvt_pk_bf16_f32 v139, v66, v67
	v_lshlrev_b32_e32 v60, 16, v140
	v_and_b32_e32 v61, 0xffff0000, v140
	v_pk_mul_f32 v[60:61], v[60:61], v[44:45]
	v_pk_fma_f32 v[60:61], v[60:61], v[18:19], v[180:181]
	v_cvt_pk_bf16_f32 v140, v60, v61
	v_lshlrev_b32_e32 v62, 16, v141
	v_and_b32_e32 v63, 0xffff0000, v141
	v_pk_mul_f32 v[62:63], v[62:63], v[44:45]
	v_pk_fma_f32 v[62:63], v[62:63], v[20:21], v[182:183]
	v_cvt_pk_bf16_f32 v141, v62, v63
	v_lshlrev_b32_e32 v64, 16, v142
	v_and_b32_e32 v65, 0xffff0000, v142
	v_pk_mul_f32 v[64:65], v[64:65], v[44:45]
	v_pk_fma_f32 v[64:65], v[64:65], v[22:23], v[184:185]
	v_cvt_pk_bf16_f32 v142, v64, v65
	v_lshlrev_b32_e32 v66, 16, v143
	v_and_b32_e32 v67, 0xffff0000, v143
	v_pk_mul_f32 v[66:67], v[66:67], v[44:45]
	v_pk_fma_f32 v[66:67], v[66:67], v[24:25], v[186:187]
	v_cvt_pk_bf16_f32 v143, v66, v67
	v_lshlrev_b32_e32 v60, 16, v144
	v_and_b32_e32 v61, 0xffff0000, v144
	v_pk_mul_f32 v[60:61], v[60:61], v[44:45]
	v_pk_fma_f32 v[60:61], v[60:61], v[26:27], v[188:189]
	v_cvt_pk_bf16_f32 v144, v60, v61
	v_lshlrev_b32_e32 v62, 16, v145
	v_and_b32_e32 v63, 0xffff0000, v145
	v_pk_mul_f32 v[62:63], v[62:63], v[44:45]
	v_pk_fma_f32 v[62:63], v[62:63], v[28:29], v[190:191]
	v_cvt_pk_bf16_f32 v145, v62, v63
	v_lshlrev_b32_e32 v64, 16, v146
	v_and_b32_e32 v65, 0xffff0000, v146
	v_pk_mul_f32 v[64:65], v[64:65], v[44:45]
	v_pk_fma_f32 v[64:65], v[64:65], v[30:31], v[192:193]
	v_cvt_pk_bf16_f32 v146, v64, v65
	v_lshlrev_b32_e32 v66, 16, v147
	v_and_b32_e32 v67, 0xffff0000, v147
	v_pk_mul_f32 v[66:67], v[66:67], v[44:45]
	v_pk_fma_f32 v[66:67], v[66:67], v[32:33], v[194:195]
	v_cvt_pk_bf16_f32 v147, v66, v67
	global_store_dwordx4 v39, v[132:135], s[20:21]
	global_store_dwordx4 v39, v[136:139], s[20:21] offset:1024
	global_store_dwordx4 v39, v[140:143], s[20:21] offset:2048
	global_store_dwordx4 v39, v[144:147], s[20:21] offset:3072
	s_add_u32 s20, s20, 0x1000
	s_addc_u32 s21, s21, 0
	s_waitcnt vmcnt(12)
	v_lshlrev_b32_e32 v60, 16, v148
	v_and_b32_e32 v61, 0xffff0000, v148
	v_pk_mul_f32 v[42:43], v[60:61], v[60:61]
	v_lshlrev_b32_e32 v62, 16, v149
	v_and_b32_e32 v63, 0xffff0000, v149
	v_pk_fma_f32 v[42:43], v[62:63], v[62:63], v[42:43]
	v_lshlrev_b32_e32 v64, 16, v150
	v_and_b32_e32 v65, 0xffff0000, v150
	v_pk_fma_f32 v[42:43], v[64:65], v[64:65], v[42:43]
	v_lshlrev_b32_e32 v66, 16, v151
	v_and_b32_e32 v67, 0xffff0000, v151
	v_pk_fma_f32 v[42:43], v[66:67], v[66:67], v[42:43]
	v_lshlrev_b32_e32 v60, 16, v152
	v_and_b32_e32 v61, 0xffff0000, v152
	v_pk_fma_f32 v[42:43], v[60:61], v[60:61], v[42:43]
	v_lshlrev_b32_e32 v62, 16, v153
	v_and_b32_e32 v63, 0xffff0000, v153
	v_pk_fma_f32 v[42:43], v[62:63], v[62:63], v[42:43]
	v_lshlrev_b32_e32 v64, 16, v154
	v_and_b32_e32 v65, 0xffff0000, v154
	v_pk_fma_f32 v[42:43], v[64:65], v[64:65], v[42:43]
	v_lshlrev_b32_e32 v66, 16, v155
	v_and_b32_e32 v67, 0xffff0000, v155
	v_pk_fma_f32 v[42:43], v[66:67], v[66:67], v[42:43]
	v_lshlrev_b32_e32 v60, 16, v156
	v_and_b32_e32 v61, 0xffff0000, v156
	v_pk_fma_f32 v[42:43], v[60:61], v[60:61], v[42:43]
	v_lshlrev_b32_e32 v62, 16, v157
	v_and_b32_e32 v63, 0xffff0000, v157
	v_pk_fma_f32 v[42:43], v[62:63], v[62:63], v[42:43]
	v_lshlrev_b32_e32 v64, 16, v158
	v_and_b32_e32 v65, 0xffff0000, v158
	v_pk_fma_f32 v[42:43], v[64:65], v[64:65], v[42:43]
	v_lshlrev_b32_e32 v66, 16, v159
	v_and_b32_e32 v67, 0xffff0000, v159
	v_pk_fma_f32 v[42:43], v[66:67], v[66:67], v[42:43]
	v_lshlrev_b32_e32 v60, 16, v160
	v_and_b32_e32 v61, 0xffff0000, v160
	v_pk_fma_f32 v[42:43], v[60:61], v[60:61], v[42:43]
	v_lshlrev_b32_e32 v62, 16, v161
	v_and_b32_e32 v63, 0xffff0000, v161
	v_pk_fma_f32 v[42:43], v[62:63], v[62:63], v[42:43]
	v_lshlrev_b32_e32 v64, 16, v162
	v_and_b32_e32 v65, 0xffff0000, v162
	v_pk_fma_f32 v[42:43], v[64:65], v[64:65], v[42:43]
	v_lshlrev_b32_e32 v66, 16, v163
	v_and_b32_e32 v67, 0xffff0000, v163
	v_pk_fma_f32 v[42:43], v[66:67], v[66:67], v[42:43]
	v_add_f32_e32 v42, v42, v43
	s_nop 1
	v_add_f32_dpp v42, v42, v42 quad_perm:[1,0,3,2] row_mask:0xf bank_mask:0xf
	s_nop 1
	v_add_f32_dpp v42, v42, v42 quad_perm:[2,3,0,1] row_mask:0xf bank_mask:0xf
	s_nop 1
	v_add_f32_dpp v42, v42, v42 row_half_mirror row_mask:0xf bank_mask:0xf
	s_nop 1
	v_add_f32_dpp v42, v42, v42 row_mirror row_mask:0xf bank_mask:0xf
	s_nop 1
	v_add_f32_dpp v42, v42, v42 row_bcast:15 row_mask:0xa bank_mask:0xf
	s_nop 1
	v_add_f32_dpp v42, v42, v42 row_bcast:31 row_mask:0xc bank_mask:0xf
	s_nop 1
	v_readlane_b32 s100, v42, 63
	s_nop 3
	v_mov_b32_e32 v44, s100
	v_fma_f32 v44, v44, v47, v224
	v_rsq_f32_e32 v45, v44
	s_nop 0
	v_mul_f32_e32 v46, v44, v45
	v_mul_f32_e32 v46, v46, v45
	v_fmaak_f32 v46, -0.5, v46, 0x3fc00000
	v_mul_f32_e32 v44, v45, v46
	v_mov_b32_e32 v45, v44
	v_lshlrev_b32_e32 v60, 16, v148
	v_and_b32_e32 v61, 0xffff0000, v148
	v_pk_mul_f32 v[60:61], v[60:61], v[44:45]
	v_pk_fma_f32 v[60:61], v[60:61], v[2:3], v[164:165]
	v_cvt_pk_bf16_f32 v148, v60, v61
	v_lshlrev_b32_e32 v62, 16, v149
	v_and_b32_e32 v63, 0xffff0000, v149
	v_pk_mul_f32 v[62:63], v[62:63], v[44:45]
	v_pk_fma_f32 v[62:63], v[62:63], v[4:5], v[166:167]
	v_cvt_pk_bf16_f32 v149, v62, v63
	v_lshlrev_b32_e32 v64, 16, v150
	v_and_b32_e32 v65, 0xffff0000, v150
	v_pk_mul_f32 v[64:65], v[64:65], v[44:45]
	v_pk_fma_f32 v[64:65], v[64:65], v[6:7], v[168:169]
	v_cvt_pk_bf16_f32 v150, v64, v65
	v_lshlrev_b32_e32 v66, 16, v151
	v_and_b32_e32 v67, 0xffff0000, v151
	v_pk_mul_f32 v[66:67], v[66:67], v[44:45]
	v_pk_fma_f32 v[66:67], v[66:67], v[8:9], v[170:171]
	v_cvt_pk_bf16_f32 v151, v66, v67
	v_lshlrev_b32_e32 v60, 16, v152
	v_and_b32_e32 v61, 0xffff0000, v152
	v_pk_mul_f32 v[60:61], v[60:61], v[44:45]
	v_pk_fma_f32 v[60:61], v[60:61], v[10:11], v[172:173]
	v_cvt_pk_bf16_f32 v152, v60, v61
	v_lshlrev_b32_e32 v62, 16, v153
	v_and_b32_e32 v63, 0xffff0000, v153
	v_pk_mul_f32 v[62:63], v[62:63], v[44:45]
	v_pk_fma_f32 v[62:63], v[62:63], v[12:13], v[174:175]
	v_cvt_pk_bf16_f32 v153, v62, v63
	v_lshlrev_b32_e32 v64, 16, v154
	v_and_b32_e32 v65, 0xffff0000, v154
	v_pk_mul_f32 v[64:65], v[64:65], v[44:45]
	v_pk_fma_f32 v[64:65], v[64:65], v[14:15], v[176:177]
	v_cvt_pk_bf16_f32 v154, v64, v65
	v_lshlrev_b32_e32 v66, 16, v155
	v_and_b32_e32 v67, 0xffff0000, v155
	v_pk_mul_f32 v[66:67], v[66:67], v[44:45]
	v_pk_fma_f32 v[66:67], v[66:67], v[16:17], v[178:179]
	v_cvt_pk_bf16_f32 v155, v66, v67
	v_lshlrev_b32_e32 v60, 16, v156
	v_and_b32_e32 v61, 0xffff0000, v156
	v_pk_mul_f32 v[60:61], v[60:61], v[44:45]
	v_pk_fma_f32 v[60:61], v[60:61], v[18:19], v[180:181]
	v_cvt_pk_bf16_f32 v156, v60, v61
	v_lshlrev_b32_e32 v62, 16, v157
	v_and_b32_e32 v63, 0xffff0000, v157
	v_pk_mul_f32 v[62:63], v[62:63], v[44:45]
	v_pk_fma_f32 v[62:63], v[62:63], v[20:21], v[182:183]
	v_cvt_pk_bf16_f32 v157, v62, v63
	v_lshlrev_b32_e32 v64, 16, v158
	v_and_b32_e32 v65, 0xffff0000, v158
	v_pk_mul_f32 v[64:65], v[64:65], v[44:45]
	v_pk_fma_f32 v[64:65], v[64:65], v[22:23], v[184:185]
	v_cvt_pk_bf16_f32 v158, v64, v65
	v_lshlrev_b32_e32 v66, 16, v159
	v_and_b32_e32 v67, 0xffff0000, v159
	v_pk_mul_f32 v[66:67], v[66:67], v[44:45]
	v_pk_fma_f32 v[66:67], v[66:67], v[24:25], v[186:187]
	v_cvt_pk_bf16_f32 v159, v66, v67
	v_lshlrev_b32_e32 v60, 16, v160
	v_and_b32_e32 v61, 0xffff0000, v160
	v_pk_mul_f32 v[60:61], v[60:61], v[44:45]
	v_pk_fma_f32 v[60:61], v[60:61], v[26:27], v[188:189]
	v_cvt_pk_bf16_f32 v160, v60, v61
	v_lshlrev_b32_e32 v62, 16, v161
	v_and_b32_e32 v63, 0xffff0000, v161
	v_pk_mul_f32 v[62:63], v[62:63], v[44:45]
	v_pk_fma_f32 v[62:63], v[62:63], v[28:29], v[190:191]
	v_cvt_pk_bf16_f32 v161, v62, v63
	v_lshlrev_b32_e32 v64, 16, v162
	v_and_b32_e32 v65, 0xffff0000, v162
	v_pk_mul_f32 v[64:65], v[64:65], v[44:45]
	v_pk_fma_f32 v[64:65], v[64:65], v[30:31], v[192:193]
	v_cvt_pk_bf16_f32 v162, v64, v65
	v_lshlrev_b32_e32 v66, 16, v163
	v_and_b32_e32 v67, 0xffff0000, v163
	v_pk_mul_f32 v[66:67], v[66:67], v[44:45]
	v_pk_fma_f32 v[66:67], v[66:67], v[32:33], v[194:195]
	v_cvt_pk_bf16_f32 v163, v66, v67
	global_store_dwordx4 v39, v[148:151], s[20:21]
	global_store_dwordx4 v39, v[152:155], s[20:21] offset:1024
	global_store_dwordx4 v39, v[156:159], s[20:21] offset:2048
	global_store_dwordx4 v39, v[160:163], s[20:21] offset:3072
	s_add_u32 s20, s20, 0x1000
	s_addc_u32 s21, s21, 0

.LBB0_902:
	s_cmp_eq_u32 s101, 0
	s_cbranch_scc1 .Lnf2_orig
	s_cmpk_lt_i32 s7, 0x4000
	s_cbranch_scc0 .Lnf2_orig
	s_add_i32 s7, s7, s42
	v_lshl_add_u64 v[36:37], v[36:37], 0, s[44:45]
	s_cmp_lt_i32 s7, s81
	s_cbranch_scc1 .LBB0_902
	s_branch .LBB0_908
